# prep_ew conv: weight quads loaded once per item, the 15 distinct input quads of a trip loaded up front; per-tap loads became register moves
# speedup vs baseline: 1.0067x; 1.0045x over previous
; DI int otid() { int t = (int)__builtin_amdgcn_workitem_id_x(); asm volatile("" : "+v"(t)); return t; }
; DI void prep_ew_item(const Params& p, int l, int item, bf16_t* lds) {
;   const int lane = otid() & 63, wid = otid() >> 6;
;   const int t0 = item * 16;
;   bf16_t* RA = (bf16_t*)(p.ws + OFF_RA);
;   const bf16_t* RC = (const bf16_t*)(p.ws + OFF_RC);
;   bf16_t* CQ = (bf16_t*)(p.ws + OFF_CQ);
;   const float* BA = (const float*)(p.ws + OFF_BA); float* GB = BA ? (float*)(p.ws + OFF_BA + 512 * 1024) : nullptr;
;     ...
;           const float* cw = p.convw + ((size_t)l * 4 + i) * 1536 + ch;
;           f32x4 c0 = *(const f32x4*)cw, c1 = *(const f32x4*)(cw + 4);
.LBB0_844:
	s_cmpk_gt_i32 s89, 0x47f
	s_mov_b64 s[26:27], -1
	s_cbranch_scc0 .LBB0_908
	v_and_b32_e32 v10, 64, v227
	v_xor_b32_e32 v9, 1, v227
	v_add_u32_e32 v10, 64, v10
	v_cmp_lt_i32_e32 vcc, v9, v10
	v_mov_b32_e32 v0, v201
	s_mov_b64 s[6:7], 0x2000
	v_cndmask_b32_e32 v9, v227, v9, vcc
	v_lshlrev_b32_e32 v58, 2, v9
	v_xor_b32_e32 v9, 2, v227
	v_cmp_lt_i32_e32 vcc, v9, v10
	v_and_b32_e32 v8, 63, v0
	v_mov_b32_e32 v0, v201
	v_cndmask_b32_e32 v9, v227, v9, vcc
	v_lshlrev_b32_e32 v59, 2, v9
	v_xor_b32_e32 v9, 4, v227
	v_cmp_lt_i32_e32 vcc, v9, v10
	v_cmp_gt_u32_e64 s[38:39], 8, v8
	v_ashrrev_i32_e32 v0, 4, v0
	v_cndmask_b32_e32 v9, v227, v9, vcc
	v_lshlrev_b32_e32 v60, 2, v9
	v_xor_b32_e32 v9, 8, v227
	v_cmp_lt_i32_e32 vcc, v9, v10
	v_and_b32_e32 v40, -4, v0
	v_lshlrev_b32_e32 v0, 2, v8
	v_cndmask_b32_e32 v9, v227, v9, vcc
	v_lshlrev_b32_e32 v61, 2, v9
	v_mov_b32_e32 v9, 0x400
	v_cmp_lt_u32_e64 s[40:41], 3, v8
	v_lshl_add_u64 v[2:3], s[20:21], 0, v[0:1]
	v_add_u32_e32 v30, s30, v8
	v_lshl_add_u64 v[4:5], s[22:23], 0, v[0:1]
	v_lshlrev_b32_e32 v0, 4, v8
	v_lshl_or_b32 v38, v8, 3, v9
	v_lshlrev_b32_e32 v8, 5, v8
	v_mov_b32_e32 v9, v1
	v_lshl_add_u64 v[8:9], s[90:91], 0, v[8:9]
	v_mov_b32_e32 v31, v1
	v_lshl_add_u64 v[6:7], s[0:1], 0, v[0:1]
	v_lshl_add_u64 v[16:17], v[8:9], 0, s[6:7]
	s_mov_b64 s[6:7], 0x3800
	v_lshlrev_b32_e32 v22, 2, v38
	v_mov_b32_e32 v23, v1
	v_readlane_b32 s60, v254, 16
	v_lshl_add_u64 v[34:35], s[2:3], 0, v[0:1]
	v_or_b32_e32 v0, 0x400, v0
	s_mov_b64 s[10:11], 0x1800
	s_mov_b64 s[8:9], 0x3000
	s_mov_b64 s[12:13], 0x4800
	v_lshl_add_u64 v[18:19], v[8:9], 0, s[6:7]
	s_mov_b64 s[6:7], 0x5000
	v_lshl_add_u64 v[22:23], s[90:91], 0, v[22:23]
	v_lshlrev_b64 v[32:33], 2, v[30:31]
	v_readlane_b32 s68, v254, 24
	v_readlane_b32 s69, v254, 25
	v_readlane_b32 s70, v254, 26
	v_readlane_b32 s71, v254, 27
	v_lshl_add_u64 v[36:37], s[0:1], 0, v[0:1]
	v_lshlrev_b32_e32 v0, 1, v38
	s_mov_b32 s4, 0
	v_lshl_add_u64 v[10:11], v[8:9], 0, s[10:11]
	v_lshl_add_u64 v[12:13], v[8:9], 0, s[8:9]
	v_lshl_add_u64 v[14:15], v[8:9], 0, s[12:13]
	v_lshl_add_u64 v[20:21], v[8:9], 0, s[6:7]
	v_lshl_add_u64 v[24:25], v[22:23], 0, s[10:11]
	v_lshl_add_u64 v[26:27], v[22:23], 0, s[8:9]
	v_lshl_add_u64 v[28:29], v[22:23], 0, s[12:13]
	s_movk_i32 s10, 0x104
	v_lshl_add_u64 v[30:31], s[70:71], 0, v[32:33]
	v_lshl_add_u64 v[32:33], s[68:69], 0, v[32:33]
	v_lshl_add_u64 v[38:39], s[0:1], 0, v[0:1]
	v_add_u32_e32 v0, s88, v40
	s_mov_b32 s5, 0x7f800000
	s_mov_b32 s11, 0x41a00000
	s_mov_b32 s12, 0x3f317217
	v_readlane_b32 s61, v254, 17
	v_readlane_b32 s62, v254, 18
	v_readlane_b32 s63, v254, 19
	v_readlane_b32 s64, v254, 20
	v_readlane_b32 s65, v254, 21
	v_readlane_b32 s66, v254, 22
	v_readlane_b32 s67, v254, 23
	v_readlane_b32 s72, v254, 28
	v_readlane_b32 s73, v254, 29
	v_readlane_b32 s74, v254, 30
	v_readlane_b32 s75, v254, 31
	global_load_dwordx4 v[76:79], v[8:9], off offset:16
	global_load_dwordx4 v[80:83], v[8:9], off
	global_load_dwordx4 v[84:87], v[10:11], off offset:16
	global_load_dwordx4 v[88:91], v[10:11], off
	global_load_dwordx4 v[92:95], v[12:13], off offset:16
	global_load_dwordx4 v[96:99], v[12:13], off
	global_load_dwordx4 v[100:103], v[14:15], off offset:16
	global_load_dwordx4 v[104:107], v[14:15], off
	global_load_dwordx4 v[108:111], v[8:9], off offset:2064
	global_load_dwordx4 v[112:115], v[8:9], off offset:2048
	global_load_dwordx4 v[116:119], v[18:19], off offset:16
	global_load_dwordx4 v[120:123], v[18:19], off
	global_load_dwordx4 v[124:127], v[16:17], off offset:16
	global_load_dwordx4 v[128:131], v[16:17], off
	global_load_dwordx4 v[132:135], v[20:21], off offset:16
	global_load_dwordx4 v[136:139], v[20:21], off
	global_load_dwordx4 v[140:143], v[22:23], off offset:16
	global_load_dwordx4 v[144:147], v[22:23], off
	global_load_dwordx4 v[148:151], v[26:27], off offset:16
	global_load_dwordx4 v[152:155], v[26:27], off
	global_load_dwordx4 v[156:159], v[24:25], off offset:16
	global_load_dwordx4 v[160:163], v[24:25], off
	global_load_dwordx4 v[164:167], v[28:29], off offset:16
	global_load_dwordx4 v[168:171], v[28:29], off
	s_branch .LBB0_848

; DI float bflo(unsigned u) { return __uint_as_float(u << 16); }
; DI float bfhi(unsigned u) { return __uint_as_float(u & 0xffff0000u); }
; DI void prep_ew_item(const Params& p, int l, int item, bf16_t* lds) {
;     ...
;     for (int part = 0; part < 3; ++part) {
;       const int ch = part * 512 + lane * 8;
;       float a[8];
; #pragma unroll
;       for (int j = 0; j < 8; ++j) a[j] = 0.f;
; #pragma unroll
;       for (int i = 0; i < 4; ++i) {
;         const int ts = tl - 3 + i;
;         if (ts >= 0) {
;           u32x4 v = *(const u32x4*)(RC + (size_t)ts * 1536 + ch); unsigned w[4] = {v.x, v.y, v.z, v.w};
;           const float* cw = p.convw + ((size_t)l * 4 + i) * 1536 + ch;
;           f32x4 c0 = *(const f32x4*)cw, c1 = *(const f32x4*)(cw + 4);
;           a[0] += bflo(w[0]) * c0[0]; a[1] += bfhi(w[0]) * c0[1]; a[2] += bflo(w[1]) * c0[2]; a[3] += bfhi(w[1]) * c0[3];
;           a[4] += bflo(w[2]) * c1[0]; a[5] += bfhi(w[2]) * c1[1]; a[6] += bflo(w[3]) * c1[2]; a[7] += bfhi(w[3]) * c1[3];
;         }
.LBB0_848:
	v_add_u32_e32 v56, s4, v0
	v_add_u32_e32 v40, 0xffffb800, v56
	v_mov_b32_e32 v50, 0
	v_add_u32_e32 v57, 0xffffb7fd, v56
	v_max_i32_e32 v175, 0, v57
	v_mad_u64_u32 v[172:173], s[98:99], v175, s57, v[6:7]
	global_load_dwordx4 v[176:179], v[172:173], off
	v_mad_u64_u32 v[172:173], s[98:99], v175, s57, v[36:37]
	global_load_dwordx4 v[192:195], v[172:173], off
	v_mad_u64_u32 v[172:173], s[98:99], v175, s57, v[38:39]
	global_load_dwordx4 v[210:213], v[172:173], off
	v_add_u32_e32 v175, 1, v57
	v_max_i32_e32 v175, 0, v175
	v_mad_u64_u32 v[172:173], s[98:99], v175, s57, v[6:7]
	global_load_dwordx4 v[180:183], v[172:173], off
	v_mad_u64_u32 v[172:173], s[98:99], v175, s57, v[36:37]
	global_load_dwordx4 v[202:205], v[172:173], off
	v_mad_u64_u32 v[172:173], s[98:99], v175, s57, v[38:39]
	global_load_dwordx4 v[222:225], v[172:173], off
	v_add_u32_e32 v175, 2, v57
	v_max_i32_e32 v175, 0, v175
	v_mad_u64_u32 v[172:173], s[98:99], v175, s57, v[6:7]
	global_load_dwordx4 v[184:187], v[172:173], off
	v_mad_u64_u32 v[172:173], s[98:99], v175, s57, v[36:37]
	global_load_dwordx4 v[196:199], v[172:173], off
	v_mad_u64_u32 v[172:173], s[98:99], v175, s57, v[38:39]
	global_load_dwordx4 v[214:217], v[172:173], off
	v_add_u32_e32 v175, 3, v57
	v_max_i32_e32 v175, 0, v175
	v_mad_u64_u32 v[172:173], s[98:99], v175, s57, v[6:7]
	global_load_dwordx4 v[188:191], v[172:173], off
	v_mad_u64_u32 v[172:173], s[98:99], v175, s57, v[36:37]
	global_load_dwordx4 v[206:209], v[172:173], off
	v_mad_u64_u32 v[172:173], s[98:99], v175, s57, v[38:39]
	global_load_dwordx4 v[228:231], v[172:173], off
	v_add_u32_e32 v175, 4, v57
	v_max_i32_e32 v175, 0, v175
	v_mad_u64_u32 v[172:173], s[98:99], v175, s57, v[6:7]
	global_load_dwordx4 v[238:241], v[172:173], off
	v_mad_u64_u32 v[172:173], s[98:99], v175, s57, v[36:37]
	global_load_dwordx4 v[242:245], v[172:173], off
	v_mad_u64_u32 v[172:173], s[98:99], v175, s57, v[38:39]
	global_load_dwordx4 v[246:249], v[172:173], off
	s_waitcnt vmcnt(0)
	v_cmp_lt_i32_e64 s[42:43], 2, v40
	v_mov_b32_e32 v51, 0
	s_waitcnt vmcnt(1)
	v_mov_b32_e32 v42, 0
	v_mov_b32_e32 v43, 0
	v_mov_b32_e32 v44, 0
	v_mov_b32_e32 v45, v50
	v_mov_b32_e32 v46, v50
	v_mov_b32_e32 v47, v50
	v_mov_b32_e32 v48, 0
	v_mov_b32_e32 v49, 0
	s_and_saveexec_b64 s[26:27], s[42:43]
	s_cbranch_execz .LBB0_850
	v_mad_u64_u32 v[42:43], s[6:7], v57, s57, v[6:7]
	v_mov_b32_e32 v46, v176
	v_mov_b32_e32 v47, v177
	v_mov_b32_e32 v48, v178
	v_mov_b32_e32 v49, v179
	v_mov_b32_e32 v50, v76
	v_mov_b32_e32 v51, v77
	v_mov_b32_e32 v52, v78
	v_mov_b32_e32 v53, v79
	s_nop 0
	v_mov_b32_e32 v42, v80
	v_mov_b32_e32 v43, v81
	v_mov_b32_e32 v44, v82
	v_mov_b32_e32 v45, v83
	v_lshlrev_b32_e32 v54, 16, v46
	v_and_b32_e32 v55, 0xffff0000, v46
	v_lshlrev_b32_e32 v46, 16, v47
	v_and_b32_e32 v47, 0xffff0000, v47
	v_pk_fma_f32 v[44:45], v[44:45], v[46:47], 0 op_sel_hi:[1,1,0]
	v_lshlrev_b32_e32 v46, 16, v48
	v_and_b32_e32 v47, 0xffff0000, v48
	v_lshlrev_b32_e32 v48, 16, v49
	v_and_b32_e32 v49, 0xffff0000, v49
	v_pk_fma_f32 v[46:47], v[50:51], v[46:47], 0 op_sel_hi:[1,1,0]
	v_pk_fma_f32 v[50:51], v[52:53], v[48:49], 0 op_sel_hi:[1,1,0]
	v_pk_fma_f32 v[42:43], v[42:43], v[54:55], 0 op_sel_hi:[1,1,0]
	v_mov_b32_e32 v48, v50
	v_mov_b32_e32 v49, v51
.LBB0_850:
	s_or_b64 exec, exec, s[26:27]
	v_add_u32_e32 v62, 0xffffb7fe, v56
	v_cmp_lt_i32_e64 s[44:45], 1, v40
	s_and_saveexec_b64 s[26:27], s[44:45]
	s_cbranch_execz .LBB0_852
	v_mad_u64_u32 v[48:49], s[6:7], v62, s57, v[6:7]
	v_mov_b32_e32 v52, v180
	v_mov_b32_e32 v53, v181
	v_mov_b32_e32 v54, v182
	v_mov_b32_e32 v55, v183
	v_mov_b32_e32 v64, v84
	v_mov_b32_e32 v65, v85
	v_mov_b32_e32 v66, v86
	v_mov_b32_e32 v67, v87
	v_mov_b32_e32 v68, v88
	v_mov_b32_e32 v69, v89
	v_mov_b32_e32 v70, v90
	v_mov_b32_e32 v71, v91
	v_lshlrev_b32_e32 v48, 16, v52
	v_and_b32_e32 v49, 0xffff0000, v52
	v_pk_fma_f32 v[42:43], v[68:69], v[48:49], v[42:43]
	v_lshlrev_b32_e32 v48, 16, v53
	v_and_b32_e32 v49, 0xffff0000, v53
	v_pk_fma_f32 v[44:45], v[70:71], v[48:49], v[44:45]
	v_lshlrev_b32_e32 v48, 16, v54
	v_and_b32_e32 v49, 0xffff0000, v54
	v_pk_fma_f32 v[46:47], v[64:65], v[48:49], v[46:47]
	v_lshlrev_b32_e32 v48, 16, v55
	v_and_b32_e32 v49, 0xffff0000, v55
	v_pk_fma_f32 v[48:49], v[66:67], v[48:49], v[50:51]
.LBB0_852:
	s_or_b64 exec, exec, s[26:27]
	v_ashrrev_i32_e32 v41, 31, v40
	v_add_u32_e32 v63, 0xffffb7ff, v56
	v_cmp_lt_i32_e64 s[46:47], 0, v40
	s_and_saveexec_b64 s[26:27], s[46:47]
	s_cbranch_execz .LBB0_854
	v_mad_u64_u32 v[50:51], s[6:7], v63, s57, v[6:7]
	v_mov_b32_e32 v50, v184
	v_mov_b32_e32 v51, v185
	v_mov_b32_e32 v52, v186
	v_mov_b32_e32 v53, v187
	s_nop 0
	v_mov_b32_e32 v64, v92
	v_mov_b32_e32 v65, v93
	v_mov_b32_e32 v66, v94
	v_mov_b32_e32 v67, v95
	v_mov_b32_e32 v68, v96
	v_mov_b32_e32 v69, v97
	v_mov_b32_e32 v70, v98
	v_mov_b32_e32 v71, v99
	v_lshlrev_b32_e32 v54, 16, v50
	v_and_b32_e32 v55, 0xffff0000, v50
	v_lshlrev_b32_e32 v50, 16, v51
	v_and_b32_e32 v51, 0xffff0000, v51
	v_pk_fma_f32 v[44:45], v[70:71], v[50:51], v[44:45]
	v_lshlrev_b32_e32 v50, 16, v52
	v_and_b32_e32 v51, 0xffff0000, v52
	v_pk_fma_f32 v[46:47], v[64:65], v[50:51], v[46:47]
	v_lshlrev_b32_e32 v50, 16, v53
	v_and_b32_e32 v51, 0xffff0000, v53
	v_pk_fma_f32 v[42:43], v[68:69], v[54:55], v[42:43]
	v_pk_fma_f32 v[48:49], v[66:67], v[50:51], v[48:49]
; DI float bflo(unsigned u) { return __uint_as_float(u << 16); }
; DI float bfhi(unsigned u) { return __uint_as_float(u & 0xffff0000u); }
; DI void prep_ew_item(const Params& p, int l, int item, bf16_t* lds) {
;     ...
;       for (int i = 0; i < 4; ++i) {
;         const int ts = tl - 3 + i;
;         if (ts >= 0) {
;           u32x4 v = *(const u32x4*)(RC + (size_t)ts * 1536 + ch); unsigned w[4] = {v.x, v.y, v.z, v.w};
;           const float* cw = p.convw + ((size_t)l * 4 + i) * 1536 + ch;
;           f32x4 c0 = *(const f32x4*)cw, c1 = *(const f32x4*)(cw + 4);
;           a[0] += bflo(w[0]) * c0[0]; a[1] += bfhi(w[0]) * c0[1]; a[2] += bflo(w[1]) * c0[2]; a[3] += bfhi(w[1]) * c0[3];
;           a[4] += bflo(w[2]) * c1[0]; a[5] += bfhi(w[2]) * c1[1]; a[6] += bflo(w[3]) * c1[2]; a[7] += bfhi(w[3]) * c1[3];
;         }
.LBB0_854:
	s_or_b64 exec, exec, s[26:27]
	v_cmp_lt_i32_e64 s[48:49], -1, v40
	s_and_saveexec_b64 s[26:27], s[48:49]
	s_cbranch_execz .LBB0_856
	v_mad_u64_u32 v[50:51], s[6:7], v40, s57, v[6:7]
	v_mov_b32_e32 v50, v188
	v_mov_b32_e32 v51, v189
	v_mov_b32_e32 v52, v190
	v_mov_b32_e32 v53, v191
	s_nop 0
	v_mov_b32_e32 v64, v100
	v_mov_b32_e32 v65, v101
	v_mov_b32_e32 v66, v102
	v_mov_b32_e32 v67, v103
	v_mov_b32_e32 v68, v104
	v_mov_b32_e32 v69, v105
	v_mov_b32_e32 v70, v106
	v_mov_b32_e32 v71, v107
	v_lshlrev_b32_e32 v54, 16, v50
	v_and_b32_e32 v55, 0xffff0000, v50
	v_lshlrev_b32_e32 v50, 16, v51
	v_and_b32_e32 v51, 0xffff0000, v51
	v_pk_fma_f32 v[44:45], v[70:71], v[50:51], v[44:45]
	v_lshlrev_b32_e32 v50, 16, v52
	v_and_b32_e32 v51, 0xffff0000, v52
	v_pk_fma_f32 v[46:47], v[64:65], v[50:51], v[46:47]
	v_lshlrev_b32_e32 v50, 16, v53
	v_and_b32_e32 v51, 0xffff0000, v53
	v_pk_fma_f32 v[42:43], v[68:69], v[54:55], v[42:43]
	v_pk_fma_f32 v[48:49], v[66:67], v[50:51], v[48:49]
; DI unsigned pk2(float lo, float hi) { f32x2_t v; v[0] = lo; v[1] = hi; bf16x2_t b = __builtin_convertvector(v, bf16x2_t); return __builtin_bit_cast(unsigned, b); }
; DI float bflo(unsigned u) { return __uint_as_float(u << 16); }
; DI float bfhi(unsigned u) { return __uint_as_float(u & 0xffff0000u); }
; DI float siluf_(float x) { return x / (1.f + __expf(-x)); }
; DI void prep_ew_item(const Params& p, int l, int item, bf16_t* lds) {
;     ...
;           u32x4 v = *(const u32x4*)(RC + (size_t)ts * 1536 + ch); unsigned w[4] = {v.x, v.y, v.z, v.w};
;           const float* cw = p.convw + ((size_t)l * 4 + i) * 1536 + ch;
;           f32x4 c0 = *(const f32x4*)cw, c1 = *(const f32x4*)(cw + 4);
;           a[0] += bflo(w[0]) * c0[0]; a[1] += bfhi(w[0]) * c0[1]; a[2] += bflo(w[1]) * c0[2]; a[3] += bfhi(w[1]) * c0[3];
;           a[4] += bflo(w[2]) * c1[0]; a[5] += bfhi(w[2]) * c1[1]; a[6] += bflo(w[3]) * c1[2]; a[7] += bfhi(w[3]) * c1[3];
;         }
;       }
;       float ss = 0.f;
; #pragma unroll
;       for (int j = 0; j < 8; ++j) { a[j] = siluf_(a[j]); ss += a[j] * a[j]; }
;       float mul = 1.f;
;       if (part < 2) {
;         ss += __shfl_xor(ss, 1); ss += __shfl_xor(ss, 2); ss += __shfl_xor(ss, 4); ss += __shfl_xor(ss, 8);
;         mul = rsqrtf(ss + EPS) * (part == 0 ? 0.08838834764831845f : 1.f);
;       }
;       u32x4 o; o.x = pk2(a[0] * mul, a[1] * mul); o.y = pk2(a[2] * mul, a[3] * mul); o.z = pk2(a[4] * mul, a[5] * mul); o.w = pk2(a[6] * mul, a[7] * mul);
;       *(u32x4*)(CQ + (size_t)t * 1536 + ch) = o;
.LBB0_856:
	s_or_b64 exec, exec, s[26:27]
	v_mul_f32_e32 v52, 0xbfb8aa3b, v44
	v_exp_f32_e32 v54, v52
	v_mul_f32_e32 v52, 0xbfb8aa3b, v45
	v_exp_f32_e32 v55, v52
	v_mul_f32_e32 v52, 0xbfb8aa3b, v46
	v_exp_f32_e32 v64, v52
	v_mul_f32_e32 v52, 0xbfb8aa3b, v47
	v_exp_f32_e32 v65, v52
	v_mul_f32_e32 v52, 0xbfb8aa3b, v48
	v_mul_f32_e32 v53, 0xbfb8aa3b, v49
	v_exp_f32_e32 v52, v52
	v_exp_f32_e32 v53, v53
	v_pk_add_f32 v[64:65], v[64:65], 1.0 op_sel_hi:[1,0]
	v_pk_add_f32 v[54:55], v[54:55], 1.0 op_sel_hi:[1,0]
	v_mul_f32_e32 v50, 0xbfb8aa3b, v42
	v_pk_add_f32 v[52:53], v[52:53], 1.0 op_sel_hi:[1,0]
	v_mul_f32_e32 v51, 0xbfb8aa3b, v43
	v_div_scale_f32 v66, s[6:7], v53, v53, v49
	v_rcp_f32_e32 v67, v66
	v_exp_f32_e32 v50, v50
	v_exp_f32_e32 v51, v51
	v_fma_f32 v68, -v66, v67, 1.0
	v_fmac_f32_e32 v67, v68, v67
	v_div_scale_f32 v68, vcc, v49, v53, v49
	v_mul_f32_e32 v69, v68, v67
	s_waitcnt vmcnt(6)
	v_fma_f32 v70, -v66, v69, v68
	v_fmac_f32_e32 v69, v70, v67
	v_fma_f32 v66, -v66, v69, v68
	v_div_fmas_f32 v66, v66, v67, v69
	v_div_fixup_f32 v49, v66, v53, v49
	v_div_scale_f32 v53, s[6:7], v52, v52, v48
	v_rcp_f32_e32 v66, v53
	v_pk_add_f32 v[50:51], v[50:51], 1.0 op_sel_hi:[1,0]
	v_fma_f32 v67, -v53, v66, 1.0
	v_fmac_f32_e32 v66, v67, v66
	v_div_scale_f32 v67, vcc, v48, v52, v48
	v_mul_f32_e32 v68, v67, v66
	v_fma_f32 v69, -v53, v68, v67
	v_fmac_f32_e32 v68, v69, v66
	v_fma_f32 v53, -v53, v68, v67
	v_div_fmas_f32 v53, v53, v66, v68
	v_div_scale_f32 v66, s[6:7], v65, v65, v47
	v_rcp_f32_e32 v67, v66
	v_div_fixup_f32 v48, v53, v52, v48
	v_pk_mul_f32 v[52:53], v[48:49], v[48:49]
	v_fma_f32 v68, -v66, v67, 1.0
	v_fmac_f32_e32 v67, v68, v67
	v_div_scale_f32 v68, vcc, v47, v65, v47
	v_mul_f32_e32 v69, v68, v67
	v_fma_f32 v70, -v66, v69, v68
	v_fmac_f32_e32 v69, v70, v67
	v_fma_f32 v66, -v66, v69, v68
	v_div_fmas_f32 v66, v66, v67, v69
	v_div_fixup_f32 v47, v66, v65, v47
	v_div_scale_f32 v65, s[6:7], v64, v64, v46
	v_rcp_f32_e32 v66, v65
	s_nop 0
	v_fma_f32 v67, -v65, v66, 1.0
	v_fmac_f32_e32 v66, v67, v66
	v_div_scale_f32 v67, vcc, v46, v64, v46
	v_mul_f32_e32 v68, v67, v66
	v_fma_f32 v69, -v65, v68, v67
	v_fmac_f32_e32 v68, v69, v66
	v_fma_f32 v65, -v65, v68, v67
	v_div_fmas_f32 v65, v65, v66, v68
	v_div_scale_f32 v66, s[6:7], v55, v55, v45
	v_rcp_f32_e32 v67, v66
	v_div_fixup_f32 v46, v65, v64, v46
	v_pk_mul_f32 v[64:65], v[46:47], v[46:47]
	v_fma_f32 v68, -v66, v67, 1.0
	v_fmac_f32_e32 v67, v68, v67
	v_div_scale_f32 v68, vcc, v45, v55, v45
	v_mul_f32_e32 v69, v68, v67
	v_fma_f32 v70, -v66, v69, v68
	v_fmac_f32_e32 v69, v70, v67
	v_fma_f32 v66, -v66, v69, v68
	v_div_fmas_f32 v66, v66, v67, v69
	v_div_fixup_f32 v55, v66, v55, v45
	v_div_scale_f32 v45, s[6:7], v54, v54, v44
	v_rcp_f32_e32 v66, v45
	s_nop 0
	v_fma_f32 v67, -v45, v66, 1.0
	v_fmac_f32_e32 v66, v67, v66
	v_div_scale_f32 v67, vcc, v44, v54, v44
	v_mul_f32_e32 v68, v67, v66
	v_fma_f32 v69, -v45, v68, v67
	v_fmac_f32_e32 v68, v69, v66
	v_fma_f32 v45, -v45, v68, v67
	v_div_fmas_f32 v45, v45, v66, v68
	v_div_scale_f32 v66, s[6:7], v51, v51, v43
	v_rcp_f32_e32 v67, v66
	v_div_fixup_f32 v54, v45, v54, v44
	v_pk_mul_f32 v[44:45], v[54:55], v[54:55]
	v_fma_f32 v68, -v66, v67, 1.0
	v_fmac_f32_e32 v67, v68, v67
	v_div_scale_f32 v68, vcc, v43, v51, v43
	v_mul_f32_e32 v69, v68, v67
	v_fma_f32 v70, -v66, v69, v68
	v_fmac_f32_e32 v69, v70, v67
	v_fma_f32 v66, -v66, v69, v68
	v_div_fmas_f32 v66, v66, v67, v69
	v_div_fixup_f32 v43, v66, v51, v43
	v_div_scale_f32 v51, s[6:7], v50, v50, v42
	v_rcp_f32_e32 v66, v51
	s_nop 0
	v_fma_f32 v67, -v51, v66, 1.0
	v_fmac_f32_e32 v66, v67, v66
	v_div_scale_f32 v67, vcc, v42, v50, v42
	v_mul_f32_e32 v68, v67, v66
	v_fma_f32 v69, -v51, v68, v67
	v_fmac_f32_e32 v68, v69, v66
	v_fma_f32 v51, -v51, v68, v67
	v_div_fmas_f32 v51, v51, v66, v68
	v_div_fixup_f32 v42, v51, v50, v42
	v_pk_mul_f32 v[50:51], v[42:43], v[42:43]
	s_nop 0
	v_add_f32_e32 v50, v50, v51
	v_add_f32_e32 v44, v44, v50
	v_add_f32_e32 v44, v45, v44
	v_add_f32_e32 v44, v64, v44
	v_add_f32_e32 v44, v65, v44
	v_add_f32_e32 v44, v52, v44
	v_add_f32_e32 v44, v53, v44
	s_nop 1
	v_add_f32_dpp v44, v44, v44 quad_perm:[1,0,3,2] row_mask:0xf bank_mask:0xf
	v_mov_b32_e32 v52, 0
	v_mov_b32_e32 v53, 0
	s_waitcnt lgkmcnt(0)
	s_nop 1
	v_add_f32_dpp v44, v44, v44 quad_perm:[2,3,0,1] row_mask:0xf bank_mask:0xf
	s_waitcnt lgkmcnt(0)
	s_nop 1
	v_add_f32_dpp v44, v44, v44 row_half_mirror row_mask:0xf bank_mask:0xf
	s_waitcnt lgkmcnt(0)
	s_nop 1
	v_add_f32_dpp v44, v44, v44 row_mirror row_mask:0xf bank_mask:0xf
	s_waitcnt lgkmcnt(0)
	v_add_f32_e32 v44, 0x358637bd, v44
	v_cmp_gt_f32_e32 vcc, s58, v44
	v_mul_f32_e32 v45, 0x4b800000, v44
	s_nop 0
	v_cndmask_b32_e32 v44, v44, v45, vcc
	v_rsq_f32_e32 v44, v44
	s_nop 0
	v_mul_f32_e32 v45, 0x45800000, v44
	v_cndmask_b32_e32 v44, v44, v45, vcc
	v_mul_f32_e32 v50, 0x3db504f3, v44
	v_pk_mul_f32 v[42:43], v[42:43], v[50:51] op_sel_hi:[1,0]
	s_nop 0
	v_cvt_pk_bf16_f32 v44, v42, v43
	v_pk_mul_f32 v[42:43], v[54:55], v[50:51] op_sel_hi:[1,0]
	s_nop 0
	v_cvt_pk_bf16_f32 v45, v42, v43
	v_pk_mul_f32 v[42:43], v[46:47], v[50:51] op_sel_hi:[1,0]
	s_nop 0
	v_cvt_pk_bf16_f32 v46, v42, v43
	v_pk_mul_f32 v[42:43], v[48:49], v[50:51] op_sel_hi:[1,0]
	v_mov_b32_e32 v48, v52
	v_cvt_pk_bf16_f32 v47, v42, v43
	v_mad_i64_i32 v[42:43], s[6:7], v40, s57, v[34:35]
	global_store_dwordx4 v[42:43], v[44:47], off
	v_mov_b32_e32 v49, v52
	v_mov_b32_e32 v50, 0
	v_mov_b32_e32 v44, 0
	v_mov_b32_e32 v45, 0
	v_mov_b32_e32 v46, 0
	v_mov_b32_e32 v47, v52
	v_mov_b32_e32 v51, 0
	s_and_saveexec_b64 s[26:27], s[42:43]
	s_cbranch_execz .LBB0_860
	v_mad_u64_u32 v[44:45], s[6:7], v57, s57, v[36:37]
	v_mov_b32_e32 v48, v192
	v_mov_b32_e32 v49, v193
	v_mov_b32_e32 v50, v194
	v_mov_b32_e32 v51, v195
	v_mov_b32_e32 v52, v108
	v_mov_b32_e32 v53, v109
	v_mov_b32_e32 v54, v110
	v_mov_b32_e32 v55, v111
	s_nop 0
	v_mov_b32_e32 v44, v112
	v_mov_b32_e32 v45, v113
	v_mov_b32_e32 v46, v114
	v_mov_b32_e32 v47, v115
	v_lshlrev_b32_e32 v64, 16, v48
	v_and_b32_e32 v65, 0xffff0000, v48
	v_lshlrev_b32_e32 v48, 16, v49
	v_and_b32_e32 v49, 0xffff0000, v49
	v_pk_fma_f32 v[46:47], v[46:47], v[48:49], 0 op_sel_hi:[1,1,0]
	v_lshlrev_b32_e32 v48, 16, v50
	v_and_b32_e32 v49, 0xffff0000, v50
	v_lshlrev_b32_e32 v50, 16, v51
	v_and_b32_e32 v51, 0xffff0000, v51
	v_pk_fma_f32 v[48:49], v[52:53], v[48:49], 0 op_sel_hi:[1,1,0]
	v_pk_fma_f32 v[52:53], v[54:55], v[50:51], 0 op_sel_hi:[1,1,0]
	v_pk_fma_f32 v[44:45], v[44:45], v[64:65], 0 op_sel_hi:[1,1,0]
	v_mov_b32_e32 v50, v52
	v_mov_b32_e32 v51, v53
	s_or_b64 exec, exec, s[26:27]
	s_and_saveexec_b64 s[26:27], s[44:45]
	s_cbranch_execnz .LBB0_861

; DI float bflo(unsigned u) { return __uint_as_float(u << 16); }
; DI float bfhi(unsigned u) { return __uint_as_float(u & 0xffff0000u); }
; DI void prep_ew_item(const Params& p, int l, int item, bf16_t* lds) {
;     ...
;       for (int i = 0; i < 4; ++i) {
;         const int ts = tl - 3 + i;
;         if (ts >= 0) {
;           u32x4 v = *(const u32x4*)(RC + (size_t)ts * 1536 + ch); unsigned w[4] = {v.x, v.y, v.z, v.w};
;           const float* cw = p.convw + ((size_t)l * 4 + i) * 1536 + ch;
;           f32x4 c0 = *(const f32x4*)cw, c1 = *(const f32x4*)(cw + 4);
;           a[0] += bflo(w[0]) * c0[0]; a[1] += bfhi(w[0]) * c0[1]; a[2] += bflo(w[1]) * c0[2]; a[3] += bfhi(w[1]) * c0[3];
;           a[4] += bflo(w[2]) * c1[0]; a[5] += bfhi(w[2]) * c1[1]; a[6] += bflo(w[3]) * c1[2]; a[7] += bfhi(w[3]) * c1[3];
;         }
.LBB0_859:
	v_mad_u64_u32 v[52:53], s[6:7], v63, s57, v[36:37]
	v_mov_b32_e32 v52, v196
	v_mov_b32_e32 v53, v197
	v_mov_b32_e32 v54, v198
	v_mov_b32_e32 v55, v199
	s_nop 0
	v_mov_b32_e32 v64, v116
	v_mov_b32_e32 v65, v117
	v_mov_b32_e32 v66, v118
	v_mov_b32_e32 v67, v119
	v_mov_b32_e32 v68, v120
	v_mov_b32_e32 v69, v121
	v_mov_b32_e32 v70, v122
	v_mov_b32_e32 v71, v123
	v_lshlrev_b32_e32 v72, 16, v52
	v_and_b32_e32 v73, 0xffff0000, v52
	v_lshlrev_b32_e32 v52, 16, v53
	v_and_b32_e32 v53, 0xffff0000, v53
	v_pk_fma_f32 v[46:47], v[70:71], v[52:53], v[46:47]
	v_lshlrev_b32_e32 v52, 16, v54
	v_and_b32_e32 v53, 0xffff0000, v54
	v_pk_fma_f32 v[48:49], v[64:65], v[52:53], v[48:49]
	v_lshlrev_b32_e32 v52, 16, v55
	v_and_b32_e32 v53, 0xffff0000, v55
	v_pk_fma_f32 v[44:45], v[68:69], v[72:73], v[44:45]
	v_pk_fma_f32 v[50:51], v[66:67], v[52:53], v[50:51]
	s_or_b64 exec, exec, s[26:27]
	s_and_saveexec_b64 s[26:27], s[48:49]
	s_cbranch_execnz .LBB0_863
	s_branch .LBB0_864

; DI float bflo(unsigned u) { return __uint_as_float(u << 16); }
; DI float bfhi(unsigned u) { return __uint_as_float(u & 0xffff0000u); }
; DI void prep_ew_item(const Params& p, int l, int item, bf16_t* lds) {
;     ...
;       for (int i = 0; i < 4; ++i) {
;         const int ts = tl - 3 + i;
;         if (ts >= 0) {
;           u32x4 v = *(const u32x4*)(RC + (size_t)ts * 1536 + ch); unsigned w[4] = {v.x, v.y, v.z, v.w};
;           const float* cw = p.convw + ((size_t)l * 4 + i) * 1536 + ch;
;           f32x4 c0 = *(const f32x4*)cw, c1 = *(const f32x4*)(cw + 4);
;           a[0] += bflo(w[0]) * c0[0]; a[1] += bfhi(w[0]) * c0[1]; a[2] += bflo(w[1]) * c0[2]; a[3] += bfhi(w[1]) * c0[3];
;           a[4] += bflo(w[2]) * c1[0]; a[5] += bfhi(w[2]) * c1[1]; a[6] += bflo(w[3]) * c1[2]; a[7] += bfhi(w[3]) * c1[3];
;         }
.LBB0_861:
	v_mad_u64_u32 v[50:51], s[6:7], v62, s57, v[36:37]
	v_mov_b32_e32 v64, v202
	v_mov_b32_e32 v65, v203
	v_mov_b32_e32 v66, v204
	v_mov_b32_e32 v67, v205
	v_mov_b32_e32 v68, v124
	v_mov_b32_e32 v69, v125
	v_mov_b32_e32 v70, v126
	v_mov_b32_e32 v71, v127
	v_mov_b32_e32 v72, v128
	v_mov_b32_e32 v73, v129
	v_mov_b32_e32 v74, v130
	v_mov_b32_e32 v75, v131
	v_lshlrev_b32_e32 v50, 16, v64
	v_and_b32_e32 v51, 0xffff0000, v64
	v_pk_fma_f32 v[44:45], v[72:73], v[50:51], v[44:45]
	v_lshlrev_b32_e32 v50, 16, v65
	v_and_b32_e32 v51, 0xffff0000, v65
	v_pk_fma_f32 v[46:47], v[74:75], v[50:51], v[46:47]
	v_lshlrev_b32_e32 v50, 16, v66
	v_and_b32_e32 v51, 0xffff0000, v66
	v_pk_fma_f32 v[48:49], v[68:69], v[50:51], v[48:49]
	v_lshlrev_b32_e32 v50, 16, v67
	v_and_b32_e32 v51, 0xffff0000, v67
	v_pk_fma_f32 v[50:51], v[70:71], v[50:51], v[52:53]
	s_or_b64 exec, exec, s[26:27]
	s_and_saveexec_b64 s[26:27], s[46:47]
	s_cbranch_execnz .LBB0_859

; DI float bflo(unsigned u) { return __uint_as_float(u << 16); }
; DI float bfhi(unsigned u) { return __uint_as_float(u & 0xffff0000u); }
; DI void prep_ew_item(const Params& p, int l, int item, bf16_t* lds) {
;     ...
;       for (int i = 0; i < 4; ++i) {
;         const int ts = tl - 3 + i;
;         if (ts >= 0) {
;           u32x4 v = *(const u32x4*)(RC + (size_t)ts * 1536 + ch); unsigned w[4] = {v.x, v.y, v.z, v.w};
;           const float* cw = p.convw + ((size_t)l * 4 + i) * 1536 + ch;
;           f32x4 c0 = *(const f32x4*)cw, c1 = *(const f32x4*)(cw + 4);
;           a[0] += bflo(w[0]) * c0[0]; a[1] += bfhi(w[0]) * c0[1]; a[2] += bflo(w[1]) * c0[2]; a[3] += bfhi(w[1]) * c0[3];
;           a[4] += bflo(w[2]) * c1[0]; a[5] += bfhi(w[2]) * c1[1]; a[6] += bflo(w[3]) * c1[2]; a[7] += bfhi(w[3]) * c1[3];
;         }
.LBB0_863:
	v_mad_u64_u32 v[52:53], s[6:7], v40, s57, v[36:37]
	v_mov_b32_e32 v52, v206
	v_mov_b32_e32 v53, v207
	v_mov_b32_e32 v54, v208
	v_mov_b32_e32 v55, v209
	s_nop 0
	v_mov_b32_e32 v64, v132
	v_mov_b32_e32 v65, v133
	v_mov_b32_e32 v66, v134
	v_mov_b32_e32 v67, v135
	v_mov_b32_e32 v68, v136
	v_mov_b32_e32 v69, v137
	v_mov_b32_e32 v70, v138
	v_mov_b32_e32 v71, v139
	v_lshlrev_b32_e32 v72, 16, v52
	v_and_b32_e32 v73, 0xffff0000, v52
	v_lshlrev_b32_e32 v52, 16, v53
	v_and_b32_e32 v53, 0xffff0000, v53
	v_pk_fma_f32 v[46:47], v[70:71], v[52:53], v[46:47]
	v_lshlrev_b32_e32 v52, 16, v54
	v_and_b32_e32 v53, 0xffff0000, v54
	v_pk_fma_f32 v[48:49], v[64:65], v[52:53], v[48:49]
	v_lshlrev_b32_e32 v52, 16, v55
	v_and_b32_e32 v53, 0xffff0000, v55
	v_pk_fma_f32 v[44:45], v[68:69], v[72:73], v[44:45]
	v_pk_fma_f32 v[50:51], v[66:67], v[52:53], v[50:51]
; DI unsigned pk2(float lo, float hi) { f32x2_t v; v[0] = lo; v[1] = hi; bf16x2_t b = __builtin_convertvector(v, bf16x2_t); return __builtin_bit_cast(unsigned, b); }
; DI float bflo(unsigned u) { return __uint_as_float(u << 16); }
; DI float bfhi(unsigned u) { return __uint_as_float(u & 0xffff0000u); }
; DI float siluf_(float x) { return x / (1.f + __expf(-x)); }
; DI void prep_ew_item(const Params& p, int l, int item, bf16_t* lds) {
;     ...
;           u32x4 v = *(const u32x4*)(RC + (size_t)ts * 1536 + ch); unsigned w[4] = {v.x, v.y, v.z, v.w};
;           const float* cw = p.convw + ((size_t)l * 4 + i) * 1536 + ch;
;           f32x4 c0 = *(const f32x4*)cw, c1 = *(const f32x4*)(cw + 4);
;           a[0] += bflo(w[0]) * c0[0]; a[1] += bfhi(w[0]) * c0[1]; a[2] += bflo(w[1]) * c0[2]; a[3] += bfhi(w[1]) * c0[3];
;           a[4] += bflo(w[2]) * c1[0]; a[5] += bfhi(w[2]) * c1[1]; a[6] += bflo(w[3]) * c1[2]; a[7] += bfhi(w[3]) * c1[3];
;         }
;       }
;       float ss = 0.f;
; #pragma unroll
;       for (int j = 0; j < 8; ++j) { a[j] = siluf_(a[j]); ss += a[j] * a[j]; }
;       float mul = 1.f;
;       if (part < 2) {
;         ss += __shfl_xor(ss, 1); ss += __shfl_xor(ss, 2); ss += __shfl_xor(ss, 4); ss += __shfl_xor(ss, 8);
;         mul = rsqrtf(ss + EPS) * (part == 0 ? 0.08838834764831845f : 1.f);
;       }
;       u32x4 o; o.x = pk2(a[0] * mul, a[1] * mul); o.y = pk2(a[2] * mul, a[3] * mul); o.z = pk2(a[4] * mul, a[5] * mul); o.w = pk2(a[6] * mul, a[7] * mul);
;       *(u32x4*)(CQ + (size_t)t * 1536 + ch) = o;
.LBB0_864:
	s_or_b64 exec, exec, s[26:27]
	v_mul_f32_e32 v54, 0xbfb8aa3b, v46
	v_exp_f32_e32 v64, v54
	v_mul_f32_e32 v54, 0xbfb8aa3b, v47
	v_exp_f32_e32 v65, v54
	v_mul_f32_e32 v54, 0xbfb8aa3b, v48
	v_exp_f32_e32 v66, v54
	v_mul_f32_e32 v54, 0xbfb8aa3b, v49
	v_exp_f32_e32 v67, v54
	v_mul_f32_e32 v54, 0xbfb8aa3b, v50
	v_mul_f32_e32 v55, 0xbfb8aa3b, v51
	v_exp_f32_e32 v54, v54
	v_exp_f32_e32 v55, v55
	v_pk_add_f32 v[66:67], v[66:67], 1.0 op_sel_hi:[1,0]
	v_pk_add_f32 v[64:65], v[64:65], 1.0 op_sel_hi:[1,0]
	v_mul_f32_e32 v52, 0xbfb8aa3b, v44
	v_pk_add_f32 v[54:55], v[54:55], 1.0 op_sel_hi:[1,0]
	v_mul_f32_e32 v53, 0xbfb8aa3b, v45
	v_div_scale_f32 v68, s[6:7], v55, v55, v51
	v_rcp_f32_e32 v69, v68
	v_exp_f32_e32 v52, v52
	v_exp_f32_e32 v53, v53
	v_fma_f32 v70, -v68, v69, 1.0
	v_fmac_f32_e32 v69, v70, v69
	v_div_scale_f32 v70, vcc, v51, v55, v51
	v_mul_f32_e32 v71, v70, v69
	v_fma_f32 v72, -v68, v71, v70
	v_fmac_f32_e32 v71, v72, v69
	v_fma_f32 v68, -v68, v71, v70
	v_div_fmas_f32 v68, v68, v69, v71
	v_div_fixup_f32 v51, v68, v55, v51
	v_div_scale_f32 v55, s[6:7], v54, v54, v50
	v_rcp_f32_e32 v68, v55
	v_pk_add_f32 v[52:53], v[52:53], 1.0 op_sel_hi:[1,0]
	v_fma_f32 v69, -v55, v68, 1.0
	v_fmac_f32_e32 v68, v69, v68
	v_div_scale_f32 v69, vcc, v50, v54, v50
	v_mul_f32_e32 v70, v69, v68
	v_fma_f32 v71, -v55, v70, v69
	v_fmac_f32_e32 v70, v71, v68
	v_fma_f32 v55, -v55, v70, v69
	v_div_fmas_f32 v55, v55, v68, v70
	v_div_scale_f32 v68, s[6:7], v67, v67, v49
	v_rcp_f32_e32 v69, v68
	v_div_fixup_f32 v50, v55, v54, v50
	v_pk_mul_f32 v[54:55], v[50:51], v[50:51]
	v_fma_f32 v70, -v68, v69, 1.0
	v_fmac_f32_e32 v69, v70, v69
	v_div_scale_f32 v70, vcc, v49, v67, v49
	v_mul_f32_e32 v71, v70, v69
	v_fma_f32 v72, -v68, v71, v70
	v_fmac_f32_e32 v71, v72, v69
	v_fma_f32 v68, -v68, v71, v70
	v_div_fmas_f32 v68, v68, v69, v71
	v_div_fixup_f32 v49, v68, v67, v49
	v_div_scale_f32 v67, s[6:7], v66, v66, v48
	v_rcp_f32_e32 v68, v67
	s_nop 0
	v_fma_f32 v69, -v67, v68, 1.0
	v_fmac_f32_e32 v68, v69, v68
	v_div_scale_f32 v69, vcc, v48, v66, v48
	v_mul_f32_e32 v70, v69, v68
	v_fma_f32 v71, -v67, v70, v69
	v_fmac_f32_e32 v70, v71, v68
	v_fma_f32 v67, -v67, v70, v69
	v_div_fmas_f32 v67, v67, v68, v70
	v_div_scale_f32 v68, s[6:7], v65, v65, v47
	v_rcp_f32_e32 v69, v68
	v_div_fixup_f32 v48, v67, v66, v48
	v_pk_mul_f32 v[66:67], v[48:49], v[48:49]
	v_fma_f32 v70, -v68, v69, 1.0
	v_fmac_f32_e32 v69, v70, v69
	v_div_scale_f32 v70, vcc, v47, v65, v47
	v_mul_f32_e32 v71, v70, v69
	v_fma_f32 v72, -v68, v71, v70
	v_fmac_f32_e32 v71, v72, v69
	v_fma_f32 v68, -v68, v71, v70
	v_div_fmas_f32 v68, v68, v69, v71
	v_div_fixup_f32 v47, v68, v65, v47
	v_div_scale_f32 v65, s[6:7], v64, v64, v46
	v_rcp_f32_e32 v68, v65
	s_nop 0
	v_fma_f32 v69, -v65, v68, 1.0
	v_fmac_f32_e32 v68, v69, v68
	v_div_scale_f32 v69, vcc, v46, v64, v46
	v_mul_f32_e32 v70, v69, v68
	v_fma_f32 v71, -v65, v70, v69
	v_fmac_f32_e32 v70, v71, v68
	v_fma_f32 v65, -v65, v70, v69
	v_div_fmas_f32 v65, v65, v68, v70
	v_div_scale_f32 v68, s[6:7], v53, v53, v45
	v_rcp_f32_e32 v69, v68
	v_div_fixup_f32 v46, v65, v64, v46
	v_pk_mul_f32 v[64:65], v[46:47], v[46:47]
	v_fma_f32 v70, -v68, v69, 1.0
	v_fmac_f32_e32 v69, v70, v69
	v_div_scale_f32 v70, vcc, v45, v53, v45
	v_mul_f32_e32 v71, v70, v69
	v_fma_f32 v72, -v68, v71, v70
	v_fmac_f32_e32 v71, v72, v69
	v_fma_f32 v68, -v68, v71, v70
	v_div_fmas_f32 v68, v68, v69, v71
	v_div_fixup_f32 v45, v68, v53, v45
	v_div_scale_f32 v53, s[6:7], v52, v52, v44
	v_rcp_f32_e32 v68, v53
	s_nop 0
	v_fma_f32 v69, -v53, v68, 1.0
	v_fmac_f32_e32 v68, v69, v68
	v_div_scale_f32 v69, vcc, v44, v52, v44
	v_mul_f32_e32 v70, v69, v68
	v_fma_f32 v71, -v53, v70, v69
	v_fmac_f32_e32 v70, v71, v68
	v_fma_f32 v53, -v53, v70, v69
	v_div_fmas_f32 v53, v53, v68, v70
	v_div_fixup_f32 v44, v53, v52, v44
	v_pk_mul_f32 v[52:53], v[44:45], v[44:45]
	s_nop 0
	v_add_f32_e32 v52, v52, v53
	v_add_f32_e32 v52, v64, v52
	v_add_f32_e32 v52, v65, v52
	v_add_f32_e32 v52, v66, v52
	v_add_f32_e32 v52, v67, v52
	v_add_f32_e32 v52, v54, v52
	v_add_f32_e32 v52, v55, v52
	s_nop 1
	v_add_f32_dpp v52, v52, v52 quad_perm:[1,0,3,2] row_mask:0xf bank_mask:0xf
	s_waitcnt lgkmcnt(0)
	s_nop 1
	v_add_f32_dpp v52, v52, v52 quad_perm:[2,3,0,1] row_mask:0xf bank_mask:0xf
	s_waitcnt lgkmcnt(0)
	s_nop 1
	v_add_f32_dpp v52, v52, v52 row_half_mirror row_mask:0xf bank_mask:0xf
	s_waitcnt lgkmcnt(0)
	s_nop 1
	v_add_f32_dpp v52, v52, v52 row_mirror row_mask:0xf bank_mask:0xf
	s_waitcnt lgkmcnt(0)
	v_add_f32_e32 v52, 0x358637bd, v52
	v_cmp_gt_f32_e32 vcc, s58, v52
	v_mul_f32_e32 v53, 0x4b800000, v52
	s_nop 0
	v_cndmask_b32_e32 v52, v52, v53, vcc
	v_rsq_f32_e32 v52, v52
	s_nop 0
	v_mul_f32_e32 v53, 0x45800000, v52
	v_cndmask_b32_e32 v52, v52, v53, vcc
	v_pk_mul_f32 v[44:45], v[44:45], v[52:53] op_sel_hi:[1,0]
	v_pk_mul_f32 v[46:47], v[46:47], v[52:53] op_sel_hi:[1,0]
	v_cvt_pk_bf16_f32 v44, v44, v45
	v_cvt_pk_bf16_f32 v45, v46, v47
	v_pk_mul_f32 v[46:47], v[48:49], v[52:53] op_sel_hi:[1,0]
	v_pk_mul_f32 v[48:49], v[50:51], v[52:53] op_sel_hi:[1,0]
	v_cvt_pk_bf16_f32 v46, v46, v47
	v_cvt_pk_bf16_f32 v47, v48, v49
	v_mov_b32_e32 v52, 0
	global_store_dwordx4 v[42:43], v[44:47], off offset:1024
	v_mov_b32_e32 v53, 0
	v_mov_b32_e32 v50, 0
	v_mov_b32_e32 v51, 0
	v_mov_b32_e32 v48, 0
	v_mov_b32_e32 v49, v52
	v_mov_b32_e32 v44, v52
	v_mov_b32_e32 v45, v52
	v_mov_b32_e32 v46, 0
	v_mov_b32_e32 v47, 0
	s_and_saveexec_b64 s[26:27], s[42:43]
	s_cbranch_execz .LBB0_868
	v_mad_u64_u32 v[44:45], s[6:7], v57, s57, v[38:39]
	v_mov_b32_e32 v44, v210
	v_mov_b32_e32 v45, v211
	v_mov_b32_e32 v46, v212
	v_mov_b32_e32 v47, v213
	s_nop 0
	v_mov_b32_e32 v52, v140
	v_mov_b32_e32 v53, v141
	v_mov_b32_e32 v54, v142
	v_mov_b32_e32 v55, v143
	v_mov_b32_e32 v64, v144
	v_mov_b32_e32 v65, v145
	v_mov_b32_e32 v66, v146
	v_mov_b32_e32 v67, v147
	v_lshlrev_b32_e32 v48, 16, v44
	v_and_b32_e32 v49, 0xffff0000, v44
	v_lshlrev_b32_e32 v44, 16, v45
	v_and_b32_e32 v45, 0xffff0000, v45
	v_pk_fma_f32 v[50:51], v[64:65], v[48:49], 0 op_sel_hi:[1,1,0]
	v_pk_fma_f32 v[48:49], v[66:67], v[44:45], 0 op_sel_hi:[1,1,0]
	v_lshlrev_b32_e32 v44, 16, v46
	v_and_b32_e32 v45, 0xffff0000, v46
	v_lshlrev_b32_e32 v46, 16, v47
	v_and_b32_e32 v47, 0xffff0000, v47
	v_pk_fma_f32 v[44:45], v[52:53], v[44:45], 0 op_sel_hi:[1,1,0]
	v_pk_fma_f32 v[52:53], v[54:55], v[46:47], 0 op_sel_hi:[1,1,0]
	s_nop 0
	v_mov_b32_e32 v46, v52
	v_mov_b32_e32 v47, v53
	s_or_b64 exec, exec, s[26:27]
	s_and_saveexec_b64 s[26:27], s[44:45]
	s_cbranch_execnz .LBB0_869

; DI float bflo(unsigned u) { return __uint_as_float(u << 16); }
; DI float bfhi(unsigned u) { return __uint_as_float(u & 0xffff0000u); }
; DI void prep_ew_item(const Params& p, int l, int item, bf16_t* lds) {
;     ...
;       for (int i = 0; i < 4; ++i) {
;         const int ts = tl - 3 + i;
;         if (ts >= 0) {
;           u32x4 v = *(const u32x4*)(RC + (size_t)ts * 1536 + ch); unsigned w[4] = {v.x, v.y, v.z, v.w};
;           const float* cw = p.convw + ((size_t)l * 4 + i) * 1536 + ch;
;           f32x4 c0 = *(const f32x4*)cw, c1 = *(const f32x4*)(cw + 4);
;           a[0] += bflo(w[0]) * c0[0]; a[1] += bfhi(w[0]) * c0[1]; a[2] += bflo(w[1]) * c0[2]; a[3] += bfhi(w[1]) * c0[3];
;           a[4] += bflo(w[2]) * c1[0]; a[5] += bfhi(w[2]) * c1[1]; a[6] += bflo(w[3]) * c1[2]; a[7] += bfhi(w[3]) * c1[3];
;         }
.LBB0_867:
	v_mad_u64_u32 v[52:53], s[6:7], v63, s57, v[38:39]
	v_mov_b32_e32 v52, v214
	v_mov_b32_e32 v53, v215
	v_mov_b32_e32 v54, v216
	v_mov_b32_e32 v55, v217
	s_nop 0
	v_mov_b32_e32 v64, v148
	v_mov_b32_e32 v65, v149
	v_mov_b32_e32 v66, v150
	v_mov_b32_e32 v67, v151
	v_mov_b32_e32 v68, v152
	v_mov_b32_e32 v69, v153
	v_mov_b32_e32 v70, v154
	v_mov_b32_e32 v71, v155
	v_lshlrev_b32_e32 v72, 16, v52
	v_and_b32_e32 v73, 0xffff0000, v52
	v_lshlrev_b32_e32 v52, 16, v53
	v_and_b32_e32 v53, 0xffff0000, v53
	v_pk_fma_f32 v[48:49], v[70:71], v[52:53], v[48:49]
	v_lshlrev_b32_e32 v52, 16, v54
	v_and_b32_e32 v53, 0xffff0000, v54
	v_pk_fma_f32 v[44:45], v[64:65], v[52:53], v[44:45]
	v_lshlrev_b32_e32 v52, 16, v55
	v_and_b32_e32 v53, 0xffff0000, v55
	v_pk_fma_f32 v[50:51], v[68:69], v[72:73], v[50:51]
	v_pk_fma_f32 v[46:47], v[66:67], v[52:53], v[46:47]
	s_or_b64 exec, exec, s[26:27]
	s_and_saveexec_b64 s[26:27], s[48:49]
	s_cbranch_execnz .LBB0_871
	s_branch .LBB0_872

; DI float bflo(unsigned u) { return __uint_as_float(u << 16); }
; DI float bfhi(unsigned u) { return __uint_as_float(u & 0xffff0000u); }
; DI void prep_ew_item(const Params& p, int l, int item, bf16_t* lds) {
;     ...
;       for (int i = 0; i < 4; ++i) {
;         const int ts = tl - 3 + i;
;         if (ts >= 0) {
;           u32x4 v = *(const u32x4*)(RC + (size_t)ts * 1536 + ch); unsigned w[4] = {v.x, v.y, v.z, v.w};
;           const float* cw = p.convw + ((size_t)l * 4 + i) * 1536 + ch;
;           f32x4 c0 = *(const f32x4*)cw, c1 = *(const f32x4*)(cw + 4);
;           a[0] += bflo(w[0]) * c0[0]; a[1] += bfhi(w[0]) * c0[1]; a[2] += bflo(w[1]) * c0[2]; a[3] += bfhi(w[1]) * c0[3];
;           a[4] += bflo(w[2]) * c1[0]; a[5] += bfhi(w[2]) * c1[1]; a[6] += bflo(w[3]) * c1[2]; a[7] += bfhi(w[3]) * c1[3];
;         }
.LBB0_869:
	v_mad_u64_u32 v[46:47], s[6:7], v62, s57, v[38:39]
	v_mov_b32_e32 v64, v222
	v_mov_b32_e32 v65, v223
	v_mov_b32_e32 v66, v224
	v_mov_b32_e32 v67, v225
	v_mov_b32_e32 v68, v156
	v_mov_b32_e32 v69, v157
	v_mov_b32_e32 v70, v158
	v_mov_b32_e32 v71, v159
	v_mov_b32_e32 v72, v160
	v_mov_b32_e32 v73, v161
	v_mov_b32_e32 v74, v162
	v_mov_b32_e32 v75, v163
	v_lshlrev_b32_e32 v46, 16, v64
	v_and_b32_e32 v47, 0xffff0000, v64
	v_pk_fma_f32 v[50:51], v[72:73], v[46:47], v[50:51]
	v_lshlrev_b32_e32 v46, 16, v65
	v_and_b32_e32 v47, 0xffff0000, v65
	v_pk_fma_f32 v[48:49], v[74:75], v[46:47], v[48:49]
	v_lshlrev_b32_e32 v46, 16, v66
	v_and_b32_e32 v47, 0xffff0000, v66
	v_pk_fma_f32 v[44:45], v[68:69], v[46:47], v[44:45]
	v_lshlrev_b32_e32 v46, 16, v67
	v_and_b32_e32 v47, 0xffff0000, v67
	v_pk_fma_f32 v[46:47], v[70:71], v[46:47], v[52:53]
	s_or_b64 exec, exec, s[26:27]
	s_and_saveexec_b64 s[26:27], s[46:47]
	s_cbranch_execnz .LBB0_867

; DI float bflo(unsigned u) { return __uint_as_float(u << 16); }
; DI float bfhi(unsigned u) { return __uint_as_float(u & 0xffff0000u); }
; DI void prep_ew_item(const Params& p, int l, int item, bf16_t* lds) {
;     ...
;       for (int i = 0; i < 4; ++i) {
;         const int ts = tl - 3 + i;
;         if (ts >= 0) {
;           u32x4 v = *(const u32x4*)(RC + (size_t)ts * 1536 + ch); unsigned w[4] = {v.x, v.y, v.z, v.w};
;           const float* cw = p.convw + ((size_t)l * 4 + i) * 1536 + ch;
;           f32x4 c0 = *(const f32x4*)cw, c1 = *(const f32x4*)(cw + 4);
;           a[0] += bflo(w[0]) * c0[0]; a[1] += bfhi(w[0]) * c0[1]; a[2] += bflo(w[1]) * c0[2]; a[3] += bfhi(w[1]) * c0[3];
;           a[4] += bflo(w[2]) * c1[0]; a[5] += bfhi(w[2]) * c1[1]; a[6] += bflo(w[3]) * c1[2]; a[7] += bfhi(w[3]) * c1[3];
;         }
.LBB0_871:
	v_mad_u64_u32 v[52:53], s[6:7], v40, s57, v[38:39]
	v_mov_b32_e32 v52, v228
	v_mov_b32_e32 v53, v229
	v_mov_b32_e32 v54, v230
	v_mov_b32_e32 v55, v231
	s_nop 0
	v_mov_b32_e32 v64, v164
	v_mov_b32_e32 v65, v165
	v_mov_b32_e32 v66, v166
	v_mov_b32_e32 v67, v167
	v_mov_b32_e32 v68, v168
	v_mov_b32_e32 v69, v169
	v_mov_b32_e32 v70, v170
	v_mov_b32_e32 v71, v171
	v_lshlrev_b32_e32 v72, 16, v52
	v_and_b32_e32 v73, 0xffff0000, v52
	v_lshlrev_b32_e32 v52, 16, v53
	v_and_b32_e32 v53, 0xffff0000, v53
	v_pk_fma_f32 v[48:49], v[70:71], v[52:53], v[48:49]
	v_lshlrev_b32_e32 v52, 16, v54
	v_and_b32_e32 v53, 0xffff0000, v54
	v_pk_fma_f32 v[44:45], v[64:65], v[52:53], v[44:45]
	v_lshlrev_b32_e32 v52, 16, v55
	v_and_b32_e32 v53, 0xffff0000, v55
	v_pk_fma_f32 v[50:51], v[68:69], v[72:73], v[50:51]
	v_pk_fma_f32 v[46:47], v[66:67], v[52:53], v[46:47]

; DI float bflo(unsigned u) { return __uint_as_float(u << 16); }
; DI float bfhi(unsigned u) { return __uint_as_float(u & 0xffff0000u); }
; DI void prep_ew_item(const Params& p, int l, int item, bf16_t* lds) {
;     ...
;     const int t = t0 + wid * 4 + rr;
;     const int tl = t;
; #pragma unroll
;     for (int part = 0; part < 3; ++part) {
;       const int ch = part * 512 + lane * 8;
;       float a[8];
; #pragma unroll
;       for (int j = 0; j < 8; ++j) a[j] = 0.f;
; #pragma unroll
;       for (int i = 0; i < 4; ++i) {
;         const int ts = tl - 3 + i;
;         if (ts >= 0) {
;           u32x4 v = *(const u32x4*)(RC + (size_t)ts * 1536 + ch); unsigned w[4] = {v.x, v.y, v.z, v.w};
;           const float* cw = p.convw + ((size_t)l * 4 + i) * 1536 + ch;
;           f32x4 c0 = *(const f32x4*)cw, c1 = *(const f32x4*)(cw + 4);
;           a[0] += bflo(w[0]) * c0[0]; a[1] += bfhi(w[0]) * c0[1]; a[2] += bflo(w[1]) * c0[2]; a[3] += bfhi(w[1]) * c0[3];
;           a[4] += bflo(w[2]) * c1[0]; a[5] += bfhi(w[2]) * c1[1]; a[6] += bflo(w[3]) * c1[2]; a[7] += bfhi(w[3]) * c1[3];
;         }
.LBB0_878:
	s_or_b64 exec, exec, s[26:27]
	v_add_u32_e32 v42, 0xffffb801, v56
	v_mov_b32_e32 v52, 0
	v_cmp_lt_i32_e64 s[42:43], 2, v42
	v_mov_b32_e32 v53, 0
	v_mov_b32_e32 v44, 0
	v_mov_b32_e32 v45, v52
	v_mov_b32_e32 v46, v52
	v_mov_b32_e32 v47, v52
	v_mov_b32_e32 v48, v52
	v_mov_b32_e32 v49, v52
	v_mov_b32_e32 v50, v52
	v_mov_b32_e32 v51, v52
	s_and_saveexec_b64 s[26:27], s[42:43]
	s_cbranch_execz .LBB0_880
	v_mad_u64_u32 v[44:45], s[6:7], v62, s57, v[6:7]
	v_mov_b32_e32 v48, v180
	v_mov_b32_e32 v49, v181
	v_mov_b32_e32 v50, v182
	v_mov_b32_e32 v51, v183
	v_mov_b32_e32 v52, v76
	v_mov_b32_e32 v53, v77
	v_mov_b32_e32 v54, v78
	v_mov_b32_e32 v55, v79
	s_nop 0
	v_mov_b32_e32 v44, v80
	v_mov_b32_e32 v45, v81
	v_mov_b32_e32 v46, v82
	v_mov_b32_e32 v47, v83
	v_lshlrev_b32_e32 v56, 16, v48
	v_and_b32_e32 v57, 0xffff0000, v48
	v_lshlrev_b32_e32 v48, 16, v49
	v_and_b32_e32 v49, 0xffff0000, v49
	v_pk_fma_f32 v[46:47], v[46:47], v[48:49], 0 op_sel_hi:[1,1,0]
	v_lshlrev_b32_e32 v48, 16, v50
	v_and_b32_e32 v49, 0xffff0000, v50
	v_lshlrev_b32_e32 v50, 16, v51
	v_and_b32_e32 v51, 0xffff0000, v51
	v_pk_fma_f32 v[48:49], v[52:53], v[48:49], 0 op_sel_hi:[1,1,0]
	v_pk_fma_f32 v[52:53], v[54:55], v[50:51], 0 op_sel_hi:[1,1,0]
	v_pk_fma_f32 v[44:45], v[44:45], v[56:57], 0 op_sel_hi:[1,1,0]
	v_mov_b32_e32 v50, v52
	v_mov_b32_e32 v51, v53
.LBB0_880:
	s_or_b64 exec, exec, s[26:27]
	v_cmp_lt_i32_e64 s[44:45], 1, v42
	s_and_saveexec_b64 s[26:27], s[44:45]
	s_cbranch_execz .LBB0_882
	v_mad_u64_u32 v[50:51], s[6:7], v63, s57, v[6:7]
	v_mov_b32_e32 v54, v184
	v_mov_b32_e32 v55, v185
	v_mov_b32_e32 v56, v186
	v_mov_b32_e32 v57, v187
	v_mov_b32_e32 v64, v84
	v_mov_b32_e32 v65, v85
	v_mov_b32_e32 v66, v86
	v_mov_b32_e32 v67, v87
	v_mov_b32_e32 v68, v88
	v_mov_b32_e32 v69, v89
	v_mov_b32_e32 v70, v90
	v_mov_b32_e32 v71, v91
	v_lshlrev_b32_e32 v50, 16, v54
	v_and_b32_e32 v51, 0xffff0000, v54
	v_pk_fma_f32 v[44:45], v[68:69], v[50:51], v[44:45]
	v_lshlrev_b32_e32 v50, 16, v55
	v_and_b32_e32 v51, 0xffff0000, v55
	v_pk_fma_f32 v[46:47], v[70:71], v[50:51], v[46:47]
	v_lshlrev_b32_e32 v50, 16, v56
	v_and_b32_e32 v51, 0xffff0000, v56
	v_pk_fma_f32 v[48:49], v[64:65], v[50:51], v[48:49]
	v_lshlrev_b32_e32 v50, 16, v57
	v_and_b32_e32 v51, 0xffff0000, v57
	v_pk_fma_f32 v[50:51], v[66:67], v[50:51], v[52:53]
.LBB0_882:
	s_or_b64 exec, exec, s[26:27]
	v_ashrrev_i32_e32 v43, 31, v42
	v_cmp_lt_i32_e64 s[46:47], 0, v42
	s_and_saveexec_b64 s[26:27], s[46:47]
	s_cbranch_execz .LBB0_884
	v_mad_u64_u32 v[52:53], s[6:7], v40, s57, v[6:7]
	v_mov_b32_e32 v52, v188
	v_mov_b32_e32 v53, v189
	v_mov_b32_e32 v54, v190
	v_mov_b32_e32 v55, v191
	s_nop 0
	v_mov_b32_e32 v64, v92
	v_mov_b32_e32 v65, v93
	v_mov_b32_e32 v66, v94
	v_mov_b32_e32 v67, v95
	v_mov_b32_e32 v68, v96
	v_mov_b32_e32 v69, v97
	v_mov_b32_e32 v70, v98
	v_mov_b32_e32 v71, v99
	v_lshlrev_b32_e32 v56, 16, v52
	v_and_b32_e32 v57, 0xffff0000, v52
	v_lshlrev_b32_e32 v52, 16, v53
	v_and_b32_e32 v53, 0xffff0000, v53
	v_pk_fma_f32 v[46:47], v[70:71], v[52:53], v[46:47]
	v_lshlrev_b32_e32 v52, 16, v54
	v_and_b32_e32 v53, 0xffff0000, v54
	v_pk_fma_f32 v[48:49], v[64:65], v[52:53], v[48:49]
	v_lshlrev_b32_e32 v52, 16, v55
	v_and_b32_e32 v53, 0xffff0000, v55
	v_pk_fma_f32 v[44:45], v[68:69], v[56:57], v[44:45]
	v_pk_fma_f32 v[50:51], v[66:67], v[52:53], v[50:51]
.LBB0_884:
	s_or_b64 exec, exec, s[26:27]
	v_cmp_lt_i32_e64 s[48:49], -1, v42
	s_and_saveexec_b64 s[26:27], s[48:49]
	s_cbranch_execz .LBB0_886
	v_mad_u64_u32 v[52:53], s[6:7], v42, s57, v[6:7]
	v_mov_b32_e32 v52, v238
	v_mov_b32_e32 v53, v239
	v_mov_b32_e32 v54, v240
	v_mov_b32_e32 v55, v241
	s_nop 0
	v_mov_b32_e32 v64, v100
	v_mov_b32_e32 v65, v101
	v_mov_b32_e32 v66, v102
	v_mov_b32_e32 v67, v103
	v_mov_b32_e32 v68, v104
	v_mov_b32_e32 v69, v105
	v_mov_b32_e32 v70, v106
	v_mov_b32_e32 v71, v107
	v_lshlrev_b32_e32 v56, 16, v52
	v_and_b32_e32 v57, 0xffff0000, v52
	v_lshlrev_b32_e32 v52, 16, v53
	v_and_b32_e32 v53, 0xffff0000, v53
	v_pk_fma_f32 v[46:47], v[70:71], v[52:53], v[46:47]
	v_lshlrev_b32_e32 v52, 16, v54
	v_and_b32_e32 v53, 0xffff0000, v54
	v_pk_fma_f32 v[48:49], v[64:65], v[52:53], v[48:49]
	v_lshlrev_b32_e32 v52, 16, v55
	v_and_b32_e32 v53, 0xffff0000, v55
	v_pk_fma_f32 v[44:45], v[68:69], v[56:57], v[44:45]
	v_pk_fma_f32 v[50:51], v[66:67], v[52:53], v[50:51]
; DI unsigned pk2(float lo, float hi) { f32x2_t v; v[0] = lo; v[1] = hi; bf16x2_t b = __builtin_convertvector(v, bf16x2_t); return __builtin_bit_cast(unsigned, b); }
; DI float bflo(unsigned u) { return __uint_as_float(u << 16); }
; DI float bfhi(unsigned u) { return __uint_as_float(u & 0xffff0000u); }
; DI float siluf_(float x) { return x / (1.f + __expf(-x)); }
; DI void prep_ew_item(const Params& p, int l, int item, bf16_t* lds) {
;     ...
;           u32x4 v = *(const u32x4*)(RC + (size_t)ts * 1536 + ch); unsigned w[4] = {v.x, v.y, v.z, v.w};
;           const float* cw = p.convw + ((size_t)l * 4 + i) * 1536 + ch;
;           f32x4 c0 = *(const f32x4*)cw, c1 = *(const f32x4*)(cw + 4);
;           a[0] += bflo(w[0]) * c0[0]; a[1] += bfhi(w[0]) * c0[1]; a[2] += bflo(w[1]) * c0[2]; a[3] += bfhi(w[1]) * c0[3];
;           a[4] += bflo(w[2]) * c1[0]; a[5] += bfhi(w[2]) * c1[1]; a[6] += bflo(w[3]) * c1[2]; a[7] += bfhi(w[3]) * c1[3];
;         }
;       }
;       float ss = 0.f;
; #pragma unroll
;       for (int j = 0; j < 8; ++j) { a[j] = siluf_(a[j]); ss += a[j] * a[j]; }
;       float mul = 1.f;
;       if (part < 2) {
;         ss += __shfl_xor(ss, 1); ss += __shfl_xor(ss, 2); ss += __shfl_xor(ss, 4); ss += __shfl_xor(ss, 8);
;         mul = rsqrtf(ss + EPS) * (part == 0 ? 0.08838834764831845f : 1.f);
;       }
;       u32x4 o; o.x = pk2(a[0] * mul, a[1] * mul); o.y = pk2(a[2] * mul, a[3] * mul); o.z = pk2(a[4] * mul, a[5] * mul); o.w = pk2(a[6] * mul, a[7] * mul);
;       *(u32x4*)(CQ + (size_t)t * 1536 + ch) = o;
.LBB0_886:
	s_or_b64 exec, exec, s[26:27]
	s_waitcnt vmcnt(1)
	v_mul_f32_e32 v41, 0xbfb8aa3b, v44
	v_exp_f32_e32 v52, v41
	v_mul_f32_e32 v41, 0xbfb8aa3b, v45
	v_exp_f32_e32 v53, v41
	v_mul_f32_e32 v41, 0xbfb8aa3b, v46
	v_exp_f32_e32 v56, v41
	v_mul_f32_e32 v41, 0xbfb8aa3b, v47
	v_exp_f32_e32 v57, v41
	v_mul_f32_e32 v41, 0xbfb8aa3b, v48
	v_exp_f32_e32 v64, v41
	v_mul_f32_e32 v41, 0xbfb8aa3b, v49
	v_exp_f32_e32 v65, v41
	v_mul_f32_e32 v41, 0xbfb8aa3b, v50
	v_exp_f32_e32 v54, v41
	v_mul_f32_e32 v41, 0xbfb8aa3b, v51
	v_exp_f32_e32 v55, v41
	v_pk_add_f32 v[64:65], v[64:65], 1.0 op_sel_hi:[1,0]
	v_pk_add_f32 v[56:57], v[56:57], 1.0 op_sel_hi:[1,0]
	v_pk_add_f32 v[52:53], v[52:53], 1.0 op_sel_hi:[1,0]
	v_pk_add_f32 v[54:55], v[54:55], 1.0 op_sel_hi:[1,0]
	s_nop 0
	v_div_scale_f32 v41, s[6:7], v55, v55, v51
	v_rcp_f32_e32 v66, v41
	s_nop 0
	v_fma_f32 v67, -v41, v66, 1.0
	v_fmac_f32_e32 v66, v67, v66
	v_div_scale_f32 v67, vcc, v51, v55, v51
	v_mul_f32_e32 v68, v67, v66
	v_fma_f32 v69, -v41, v68, v67
	v_fmac_f32_e32 v68, v69, v66
	v_fma_f32 v41, -v41, v68, v67
	v_div_fmas_f32 v41, v41, v66, v68
	v_div_fixup_f32 v51, v41, v55, v51
	v_div_scale_f32 v41, s[6:7], v54, v54, v50
	v_rcp_f32_e32 v55, v41
	s_nop 0
	v_fma_f32 v66, -v41, v55, 1.0
	v_fmac_f32_e32 v55, v66, v55
	v_div_scale_f32 v66, vcc, v50, v54, v50
	v_mul_f32_e32 v67, v66, v55
	v_fma_f32 v68, -v41, v67, v66
	v_fmac_f32_e32 v67, v68, v55
	v_fma_f32 v41, -v41, v67, v66
	v_div_fmas_f32 v41, v41, v55, v67
	v_div_fixup_f32 v50, v41, v54, v50
	v_div_scale_f32 v41, s[6:7], v65, v65, v49
	v_rcp_f32_e32 v66, v41
	v_pk_mul_f32 v[54:55], v[50:51], v[50:51]
	v_fma_f32 v67, -v41, v66, 1.0
	v_fmac_f32_e32 v66, v67, v66
	v_div_scale_f32 v67, vcc, v49, v65, v49
	v_mul_f32_e32 v68, v67, v66
	v_fma_f32 v69, -v41, v68, v67
	v_fmac_f32_e32 v68, v69, v66
	v_fma_f32 v41, -v41, v68, v67
	v_div_fmas_f32 v41, v41, v66, v68
	v_div_fixup_f32 v49, v41, v65, v49
	v_div_scale_f32 v41, s[6:7], v64, v64, v48
	v_rcp_f32_e32 v65, v41
	s_nop 0
	v_fma_f32 v66, -v41, v65, 1.0
	v_fmac_f32_e32 v65, v66, v65
	v_div_scale_f32 v66, vcc, v48, v64, v48
	v_mul_f32_e32 v67, v66, v65
	v_fma_f32 v68, -v41, v67, v66
	v_fmac_f32_e32 v67, v68, v65
	v_fma_f32 v41, -v41, v67, v66
	v_div_fmas_f32 v41, v41, v65, v67
	v_div_fixup_f32 v48, v41, v64, v48
	v_div_scale_f32 v41, s[6:7], v57, v57, v47
	v_rcp_f32_e32 v66, v41
	v_pk_mul_f32 v[64:65], v[48:49], v[48:49]
	v_fma_f32 v67, -v41, v66, 1.0
	v_fmac_f32_e32 v66, v67, v66
	v_div_scale_f32 v67, vcc, v47, v57, v47
	v_mul_f32_e32 v68, v67, v66
	v_fma_f32 v69, -v41, v68, v67
	v_fmac_f32_e32 v68, v69, v66
	v_fma_f32 v41, -v41, v68, v67
	v_div_fmas_f32 v41, v41, v66, v68
	v_div_fixup_f32 v57, v41, v57, v47
	v_div_scale_f32 v41, s[6:7], v56, v56, v46
	v_rcp_f32_e32 v47, v41
	s_nop 0
	v_fma_f32 v66, -v41, v47, 1.0
	v_fmac_f32_e32 v47, v66, v47
	v_div_scale_f32 v66, vcc, v46, v56, v46
	v_mul_f32_e32 v67, v66, v47
	v_fma_f32 v68, -v41, v67, v66
	v_fmac_f32_e32 v67, v68, v47
	v_fma_f32 v41, -v41, v67, v66
	v_div_fmas_f32 v41, v41, v47, v67
	v_div_fixup_f32 v56, v41, v56, v46
	v_div_scale_f32 v41, s[6:7], v53, v53, v45
	v_rcp_f32_e32 v66, v41
	v_pk_mul_f32 v[46:47], v[56:57], v[56:57]
	v_fma_f32 v67, -v41, v66, 1.0
	v_fmac_f32_e32 v66, v67, v66
	v_div_scale_f32 v67, vcc, v45, v53, v45
	v_mul_f32_e32 v68, v67, v66
	v_fma_f32 v69, -v41, v68, v67
	v_fmac_f32_e32 v68, v69, v66
	v_fma_f32 v41, -v41, v68, v67
	v_div_fmas_f32 v41, v41, v66, v68
	v_div_fixup_f32 v45, v41, v53, v45
	v_div_scale_f32 v41, s[6:7], v52, v52, v44
	v_rcp_f32_e32 v53, v41
	s_nop 0
	v_fma_f32 v66, -v41, v53, 1.0
	v_fmac_f32_e32 v53, v66, v53
	v_div_scale_f32 v66, vcc, v44, v52, v44
	v_mul_f32_e32 v67, v66, v53
	v_fma_f32 v68, -v41, v67, v66
	v_fmac_f32_e32 v67, v68, v53
	v_fma_f32 v41, -v41, v67, v66
	v_div_fmas_f32 v41, v41, v53, v67
	v_div_fixup_f32 v44, v41, v52, v44
	v_pk_mul_f32 v[52:53], v[44:45], v[44:45]
	s_nop 0
	v_add_f32_e32 v41, v52, v53
	v_add_f32_e32 v41, v46, v41
	v_add_f32_e32 v41, v47, v41
	v_add_f32_e32 v41, v64, v41
	v_add_f32_e32 v41, v65, v41
	v_add_f32_e32 v41, v54, v41
	v_add_f32_e32 v41, v55, v41
	s_nop 1
	v_add_f32_dpp v41, v41, v41 quad_perm:[1,0,3,2] row_mask:0xf bank_mask:0xf
	v_mov_b32_e32 v54, 0
	v_mov_b32_e32 v55, 0
	s_waitcnt lgkmcnt(0)
	s_nop 1
	v_add_f32_dpp v41, v41, v41 quad_perm:[2,3,0,1] row_mask:0xf bank_mask:0xf
	s_waitcnt lgkmcnt(0)
	s_nop 1
	v_add_f32_dpp v41, v41, v41 row_half_mirror row_mask:0xf bank_mask:0xf
	s_waitcnt lgkmcnt(0)
	s_nop 1
	v_add_f32_dpp v41, v41, v41 row_mirror row_mask:0xf bank_mask:0xf
	s_waitcnt lgkmcnt(0)
	v_add_f32_e32 v41, 0x358637bd, v41
	v_cmp_gt_f32_e32 vcc, s58, v41
	v_mul_f32_e32 v46, 0x4b800000, v41
	s_nop 0
	v_cndmask_b32_e32 v41, v41, v46, vcc
	v_rsq_f32_e32 v41, v41
	s_nop 0
	v_mul_f32_e32 v46, 0x45800000, v41
	v_cndmask_b32_e32 v41, v41, v46, vcc
	v_mul_f32_e32 v52, 0x3db504f3, v41
	v_pk_mul_f32 v[44:45], v[44:45], v[52:53] op_sel_hi:[1,0]
	s_nop 0
	v_cvt_pk_bf16_f32 v46, v44, v45
	v_pk_mul_f32 v[44:45], v[56:57], v[52:53] op_sel_hi:[1,0]
	s_nop 0
	v_cvt_pk_bf16_f32 v47, v44, v45
	v_pk_mul_f32 v[44:45], v[48:49], v[52:53] op_sel_hi:[1,0]
	s_nop 0
	v_cvt_pk_bf16_f32 v48, v44, v45
	v_pk_mul_f32 v[44:45], v[50:51], v[52:53] op_sel_hi:[1,0]
	v_mov_b32_e32 v50, v54
	v_cvt_pk_bf16_f32 v49, v44, v45
	v_mad_i64_i32 v[44:45], s[6:7], v42, s57, v[34:35]
	global_store_dwordx4 v[44:45], v[46:49], off
	v_mov_b32_e32 v51, v54
	v_mov_b32_e32 v52, 0
	v_mov_b32_e32 v46, 0
	v_mov_b32_e32 v47, 0
	v_mov_b32_e32 v48, 0
	v_mov_b32_e32 v49, v54
	v_mov_b32_e32 v53, 0
	s_and_saveexec_b64 s[26:27], s[42:43]
	s_cbranch_execz .LBB0_890
	v_mad_u64_u32 v[46:47], s[6:7], v62, s57, v[36:37]
	v_mov_b32_e32 v50, v202
	v_mov_b32_e32 v51, v203
	v_mov_b32_e32 v52, v204
	v_mov_b32_e32 v53, v205
	v_mov_b32_e32 v54, v108
	v_mov_b32_e32 v55, v109
	v_mov_b32_e32 v56, v110
	v_mov_b32_e32 v57, v111
	s_nop 0
	v_mov_b32_e32 v46, v112
	v_mov_b32_e32 v47, v113
	v_mov_b32_e32 v48, v114
	v_mov_b32_e32 v49, v115
	v_lshlrev_b32_e32 v64, 16, v50
	v_and_b32_e32 v65, 0xffff0000, v50
	v_lshlrev_b32_e32 v50, 16, v51
	v_and_b32_e32 v51, 0xffff0000, v51
	v_pk_fma_f32 v[48:49], v[48:49], v[50:51], 0 op_sel_hi:[1,1,0]
	v_lshlrev_b32_e32 v50, 16, v52
	v_and_b32_e32 v51, 0xffff0000, v52
	v_lshlrev_b32_e32 v52, 16, v53
	v_and_b32_e32 v53, 0xffff0000, v53
	v_pk_fma_f32 v[50:51], v[54:55], v[50:51], 0 op_sel_hi:[1,1,0]
	v_pk_fma_f32 v[54:55], v[56:57], v[52:53], 0 op_sel_hi:[1,1,0]
	v_pk_fma_f32 v[46:47], v[46:47], v[64:65], 0 op_sel_hi:[1,1,0]
	v_mov_b32_e32 v52, v54
	v_mov_b32_e32 v53, v55
	s_or_b64 exec, exec, s[26:27]
	s_and_saveexec_b64 s[26:27], s[44:45]
	s_cbranch_execnz .LBB0_891

; DI float bflo(unsigned u) { return __uint_as_float(u << 16); }
; DI float bfhi(unsigned u) { return __uint_as_float(u & 0xffff0000u); }
; DI void prep_ew_item(const Params& p, int l, int item, bf16_t* lds) {
;     ...
;       for (int i = 0; i < 4; ++i) {
;         const int ts = tl - 3 + i;
;         if (ts >= 0) {
;           u32x4 v = *(const u32x4*)(RC + (size_t)ts * 1536 + ch); unsigned w[4] = {v.x, v.y, v.z, v.w};
;           const float* cw = p.convw + ((size_t)l * 4 + i) * 1536 + ch;
;           f32x4 c0 = *(const f32x4*)cw, c1 = *(const f32x4*)(cw + 4);
;           a[0] += bflo(w[0]) * c0[0]; a[1] += bfhi(w[0]) * c0[1]; a[2] += bflo(w[1]) * c0[2]; a[3] += bfhi(w[1]) * c0[3];
;           a[4] += bflo(w[2]) * c1[0]; a[5] += bfhi(w[2]) * c1[1]; a[6] += bflo(w[3]) * c1[2]; a[7] += bfhi(w[3]) * c1[3];
;         }
.LBB0_889:
	v_mad_u64_u32 v[54:55], s[6:7], v40, s57, v[36:37]
	v_mov_b32_e32 v54, v206
	v_mov_b32_e32 v55, v207
	v_mov_b32_e32 v56, v208
	v_mov_b32_e32 v57, v209
	s_nop 0
	v_mov_b32_e32 v64, v116
	v_mov_b32_e32 v65, v117
	v_mov_b32_e32 v66, v118
	v_mov_b32_e32 v67, v119
	v_mov_b32_e32 v68, v120
	v_mov_b32_e32 v69, v121
	v_mov_b32_e32 v70, v122
	v_mov_b32_e32 v71, v123
	v_lshlrev_b32_e32 v72, 16, v54
	v_and_b32_e32 v73, 0xffff0000, v54
	v_lshlrev_b32_e32 v54, 16, v55
	v_and_b32_e32 v55, 0xffff0000, v55
	v_pk_fma_f32 v[48:49], v[70:71], v[54:55], v[48:49]
	v_lshlrev_b32_e32 v54, 16, v56
	v_and_b32_e32 v55, 0xffff0000, v56
	v_pk_fma_f32 v[50:51], v[64:65], v[54:55], v[50:51]
	v_lshlrev_b32_e32 v54, 16, v57
	v_and_b32_e32 v55, 0xffff0000, v57
	v_pk_fma_f32 v[46:47], v[68:69], v[72:73], v[46:47]
	v_pk_fma_f32 v[52:53], v[66:67], v[54:55], v[52:53]
	s_or_b64 exec, exec, s[26:27]
	s_and_saveexec_b64 s[26:27], s[48:49]
	s_cbranch_execnz .LBB0_893
	s_branch .LBB0_894

; DI float bflo(unsigned u) { return __uint_as_float(u << 16); }
; DI float bfhi(unsigned u) { return __uint_as_float(u & 0xffff0000u); }
; DI void prep_ew_item(const Params& p, int l, int item, bf16_t* lds) {
;     ...
;       for (int i = 0; i < 4; ++i) {
;         const int ts = tl - 3 + i;
;         if (ts >= 0) {
;           u32x4 v = *(const u32x4*)(RC + (size_t)ts * 1536 + ch); unsigned w[4] = {v.x, v.y, v.z, v.w};
;           const float* cw = p.convw + ((size_t)l * 4 + i) * 1536 + ch;
;           f32x4 c0 = *(const f32x4*)cw, c1 = *(const f32x4*)(cw + 4);
;           a[0] += bflo(w[0]) * c0[0]; a[1] += bfhi(w[0]) * c0[1]; a[2] += bflo(w[1]) * c0[2]; a[3] += bfhi(w[1]) * c0[3];
;           a[4] += bflo(w[2]) * c1[0]; a[5] += bfhi(w[2]) * c1[1]; a[6] += bflo(w[3]) * c1[2]; a[7] += bfhi(w[3]) * c1[3];
;         }
.LBB0_891:
	v_mad_u64_u32 v[52:53], s[6:7], v63, s57, v[36:37]
	v_mov_b32_e32 v64, v196
	v_mov_b32_e32 v65, v197
	v_mov_b32_e32 v66, v198
	v_mov_b32_e32 v67, v199
	v_mov_b32_e32 v68, v124
	v_mov_b32_e32 v69, v125
	v_mov_b32_e32 v70, v126
	v_mov_b32_e32 v71, v127
	v_mov_b32_e32 v72, v128
	v_mov_b32_e32 v73, v129
	v_mov_b32_e32 v74, v130
	v_mov_b32_e32 v75, v131
	v_lshlrev_b32_e32 v52, 16, v64
	v_and_b32_e32 v53, 0xffff0000, v64
	v_pk_fma_f32 v[46:47], v[72:73], v[52:53], v[46:47]
	v_lshlrev_b32_e32 v52, 16, v65
	v_and_b32_e32 v53, 0xffff0000, v65
	v_pk_fma_f32 v[48:49], v[74:75], v[52:53], v[48:49]
	v_lshlrev_b32_e32 v52, 16, v66
	v_and_b32_e32 v53, 0xffff0000, v66
	v_pk_fma_f32 v[50:51], v[68:69], v[52:53], v[50:51]
	v_lshlrev_b32_e32 v52, 16, v67
	v_and_b32_e32 v53, 0xffff0000, v67
	v_pk_fma_f32 v[52:53], v[70:71], v[52:53], v[54:55]
	s_or_b64 exec, exec, s[26:27]
	s_and_saveexec_b64 s[26:27], s[46:47]
	s_cbranch_execnz .LBB0_889

; DI float bflo(unsigned u) { return __uint_as_float(u << 16); }
; DI float bfhi(unsigned u) { return __uint_as_float(u & 0xffff0000u); }
; DI void prep_ew_item(const Params& p, int l, int item, bf16_t* lds) {
;     ...
;       for (int i = 0; i < 4; ++i) {
;         const int ts = tl - 3 + i;
;         if (ts >= 0) {
;           u32x4 v = *(const u32x4*)(RC + (size_t)ts * 1536 + ch); unsigned w[4] = {v.x, v.y, v.z, v.w};
;           const float* cw = p.convw + ((size_t)l * 4 + i) * 1536 + ch;
;           f32x4 c0 = *(const f32x4*)cw, c1 = *(const f32x4*)(cw + 4);
;           a[0] += bflo(w[0]) * c0[0]; a[1] += bfhi(w[0]) * c0[1]; a[2] += bflo(w[1]) * c0[2]; a[3] += bfhi(w[1]) * c0[3];
;           a[4] += bflo(w[2]) * c1[0]; a[5] += bfhi(w[2]) * c1[1]; a[6] += bflo(w[3]) * c1[2]; a[7] += bfhi(w[3]) * c1[3];
;         }
.LBB0_893:
	v_mad_u64_u32 v[54:55], s[6:7], v42, s57, v[36:37]
	v_mov_b32_e32 v54, v242
	v_mov_b32_e32 v55, v243
	v_mov_b32_e32 v56, v244
	v_mov_b32_e32 v57, v245
	s_nop 0
	v_mov_b32_e32 v64, v132
	v_mov_b32_e32 v65, v133
	v_mov_b32_e32 v66, v134
	v_mov_b32_e32 v67, v135
	v_mov_b32_e32 v68, v136
	v_mov_b32_e32 v69, v137
	v_mov_b32_e32 v70, v138
	v_mov_b32_e32 v71, v139
	v_lshlrev_b32_e32 v72, 16, v54
	v_and_b32_e32 v73, 0xffff0000, v54
	v_lshlrev_b32_e32 v54, 16, v55
	v_and_b32_e32 v55, 0xffff0000, v55
	v_pk_fma_f32 v[48:49], v[70:71], v[54:55], v[48:49]
	v_lshlrev_b32_e32 v54, 16, v56
	v_and_b32_e32 v55, 0xffff0000, v56
	v_pk_fma_f32 v[50:51], v[64:65], v[54:55], v[50:51]
	v_lshlrev_b32_e32 v54, 16, v57
	v_and_b32_e32 v55, 0xffff0000, v57
	v_pk_fma_f32 v[46:47], v[68:69], v[72:73], v[46:47]
	v_pk_fma_f32 v[52:53], v[66:67], v[54:55], v[52:53]
; DI unsigned pk2(float lo, float hi) { f32x2_t v; v[0] = lo; v[1] = hi; bf16x2_t b = __builtin_convertvector(v, bf16x2_t); return __builtin_bit_cast(unsigned, b); }
; DI float bflo(unsigned u) { return __uint_as_float(u << 16); }
; DI float bfhi(unsigned u) { return __uint_as_float(u & 0xffff0000u); }
; DI float siluf_(float x) { return x / (1.f + __expf(-x)); }
; DI void prep_ew_item(const Params& p, int l, int item, bf16_t* lds) {
;     ...
;           u32x4 v = *(const u32x4*)(RC + (size_t)ts * 1536 + ch); unsigned w[4] = {v.x, v.y, v.z, v.w};
;           const float* cw = p.convw + ((size_t)l * 4 + i) * 1536 + ch;
;           f32x4 c0 = *(const f32x4*)cw, c1 = *(const f32x4*)(cw + 4);
;           a[0] += bflo(w[0]) * c0[0]; a[1] += bfhi(w[0]) * c0[1]; a[2] += bflo(w[1]) * c0[2]; a[3] += bfhi(w[1]) * c0[3];
;           a[4] += bflo(w[2]) * c1[0]; a[5] += bfhi(w[2]) * c1[1]; a[6] += bflo(w[3]) * c1[2]; a[7] += bfhi(w[3]) * c1[3];
;         }
;       }
;       float ss = 0.f;
; #pragma unroll
;       for (int j = 0; j < 8; ++j) { a[j] = siluf_(a[j]); ss += a[j] * a[j]; }
;       float mul = 1.f;
;       if (part < 2) {
;         ss += __shfl_xor(ss, 1); ss += __shfl_xor(ss, 2); ss += __shfl_xor(ss, 4); ss += __shfl_xor(ss, 8);
;         mul = rsqrtf(ss + EPS) * (part == 0 ? 0.08838834764831845f : 1.f);
;       }
;       u32x4 o; o.x = pk2(a[0] * mul, a[1] * mul); o.y = pk2(a[2] * mul, a[3] * mul); o.z = pk2(a[4] * mul, a[5] * mul); o.w = pk2(a[6] * mul, a[7] * mul);
;       *(u32x4*)(CQ + (size_t)t * 1536 + ch) = o;
.LBB0_894:
	s_or_b64 exec, exec, s[26:27]
	v_mul_f32_e32 v41, 0xbfb8aa3b, v46
	v_exp_f32_e32 v54, v41
	v_mul_f32_e32 v41, 0xbfb8aa3b, v47
	v_exp_f32_e32 v55, v41
	v_mul_f32_e32 v41, 0xbfb8aa3b, v48
	v_exp_f32_e32 v64, v41
	v_mul_f32_e32 v41, 0xbfb8aa3b, v49
	v_exp_f32_e32 v65, v41
	v_mul_f32_e32 v41, 0xbfb8aa3b, v50
	v_exp_f32_e32 v66, v41
	v_mul_f32_e32 v41, 0xbfb8aa3b, v51
	v_exp_f32_e32 v67, v41
	v_mul_f32_e32 v41, 0xbfb8aa3b, v52
	v_exp_f32_e32 v56, v41
	v_mul_f32_e32 v41, 0xbfb8aa3b, v53
	v_exp_f32_e32 v57, v41
	v_pk_add_f32 v[66:67], v[66:67], 1.0 op_sel_hi:[1,0]
	v_pk_add_f32 v[64:65], v[64:65], 1.0 op_sel_hi:[1,0]
	v_pk_add_f32 v[54:55], v[54:55], 1.0 op_sel_hi:[1,0]
	v_pk_add_f32 v[56:57], v[56:57], 1.0 op_sel_hi:[1,0]
	s_nop 0
	v_div_scale_f32 v41, s[6:7], v57, v57, v53
	v_rcp_f32_e32 v68, v41
	s_nop 0
	v_fma_f32 v69, -v41, v68, 1.0
	v_fmac_f32_e32 v68, v69, v68
	v_div_scale_f32 v69, vcc, v53, v57, v53
	v_mul_f32_e32 v70, v69, v68
	v_fma_f32 v71, -v41, v70, v69
	v_fmac_f32_e32 v70, v71, v68
	v_fma_f32 v41, -v41, v70, v69
	v_div_fmas_f32 v41, v41, v68, v70
	v_div_fixup_f32 v53, v41, v57, v53
	v_div_scale_f32 v41, s[6:7], v56, v56, v52
	v_rcp_f32_e32 v57, v41
	s_nop 0
	v_fma_f32 v68, -v41, v57, 1.0
	v_fmac_f32_e32 v57, v68, v57
	v_div_scale_f32 v68, vcc, v52, v56, v52
	v_mul_f32_e32 v69, v68, v57
	v_fma_f32 v70, -v41, v69, v68
	v_fmac_f32_e32 v69, v70, v57
	v_fma_f32 v41, -v41, v69, v68
	v_div_fmas_f32 v41, v41, v57, v69
	v_div_fixup_f32 v52, v41, v56, v52
	v_div_scale_f32 v41, s[6:7], v67, v67, v51
	v_rcp_f32_e32 v68, v41
	v_pk_mul_f32 v[56:57], v[52:53], v[52:53]
	v_fma_f32 v69, -v41, v68, 1.0
	v_fmac_f32_e32 v68, v69, v68
	v_div_scale_f32 v69, vcc, v51, v67, v51
	v_mul_f32_e32 v70, v69, v68
	v_fma_f32 v71, -v41, v70, v69
	v_fmac_f32_e32 v70, v71, v68
	v_fma_f32 v41, -v41, v70, v69
	v_div_fmas_f32 v41, v41, v68, v70
	v_div_fixup_f32 v51, v41, v67, v51
	v_div_scale_f32 v41, s[6:7], v66, v66, v50
	v_rcp_f32_e32 v67, v41
	s_nop 0
	v_fma_f32 v68, -v41, v67, 1.0
	v_fmac_f32_e32 v67, v68, v67
	v_div_scale_f32 v68, vcc, v50, v66, v50
	v_mul_f32_e32 v69, v68, v67
	v_fma_f32 v70, -v41, v69, v68
	v_fmac_f32_e32 v69, v70, v67
	v_fma_f32 v41, -v41, v69, v68
	v_div_fmas_f32 v41, v41, v67, v69
	v_div_fixup_f32 v50, v41, v66, v50
	v_div_scale_f32 v41, s[6:7], v65, v65, v49
	v_rcp_f32_e32 v68, v41
	v_pk_mul_f32 v[66:67], v[50:51], v[50:51]
	v_fma_f32 v69, -v41, v68, 1.0
	v_fmac_f32_e32 v68, v69, v68
	v_div_scale_f32 v69, vcc, v49, v65, v49
	v_mul_f32_e32 v70, v69, v68
	v_fma_f32 v71, -v41, v70, v69
	v_fmac_f32_e32 v70, v71, v68
	v_fma_f32 v41, -v41, v70, v69
	v_div_fmas_f32 v41, v41, v68, v70
	v_div_fixup_f32 v49, v41, v65, v49
	v_div_scale_f32 v41, s[6:7], v64, v64, v48
	v_rcp_f32_e32 v65, v41
	s_nop 0
	v_fma_f32 v68, -v41, v65, 1.0
	v_fmac_f32_e32 v65, v68, v65
	v_div_scale_f32 v68, vcc, v48, v64, v48
	v_mul_f32_e32 v69, v68, v65
	v_fma_f32 v70, -v41, v69, v68
	v_fmac_f32_e32 v69, v70, v65
	v_fma_f32 v41, -v41, v69, v68
	v_div_fmas_f32 v41, v41, v65, v69
	v_div_fixup_f32 v48, v41, v64, v48
	v_div_scale_f32 v41, s[6:7], v55, v55, v47
	v_rcp_f32_e32 v68, v41
	v_pk_mul_f32 v[64:65], v[48:49], v[48:49]
	v_fma_f32 v69, -v41, v68, 1.0
	v_fmac_f32_e32 v68, v69, v68
	v_div_scale_f32 v69, vcc, v47, v55, v47
	v_mul_f32_e32 v70, v69, v68
	v_fma_f32 v71, -v41, v70, v69
	v_fmac_f32_e32 v70, v71, v68
	v_fma_f32 v41, -v41, v70, v69
	v_div_fmas_f32 v41, v41, v68, v70
	v_div_fixup_f32 v47, v41, v55, v47
	v_div_scale_f32 v41, s[6:7], v54, v54, v46
	v_rcp_f32_e32 v55, v41
	s_nop 0
	v_fma_f32 v68, -v41, v55, 1.0
	v_fmac_f32_e32 v55, v68, v55
	v_div_scale_f32 v68, vcc, v46, v54, v46
	v_mul_f32_e32 v69, v68, v55
	v_fma_f32 v70, -v41, v69, v68
	v_fmac_f32_e32 v69, v70, v55
	v_fma_f32 v41, -v41, v69, v68
	v_div_fmas_f32 v41, v41, v55, v69
	v_div_fixup_f32 v46, v41, v54, v46
	v_pk_mul_f32 v[54:55], v[46:47], v[46:47]
	s_nop 0
	v_add_f32_e32 v41, v54, v55
	v_add_f32_e32 v41, v64, v41
	v_add_f32_e32 v41, v65, v41
	v_add_f32_e32 v41, v66, v41
	v_add_f32_e32 v41, v67, v41
	v_add_f32_e32 v41, v56, v41
	v_add_f32_e32 v41, v57, v41
	s_nop 1
	v_add_f32_dpp v41, v41, v41 quad_perm:[1,0,3,2] row_mask:0xf bank_mask:0xf
	s_waitcnt lgkmcnt(0)
	s_nop 1
	v_add_f32_dpp v41, v41, v41 quad_perm:[2,3,0,1] row_mask:0xf bank_mask:0xf
	s_waitcnt lgkmcnt(0)
	s_nop 1
	v_add_f32_dpp v41, v41, v41 row_half_mirror row_mask:0xf bank_mask:0xf
	s_waitcnt lgkmcnt(0)
	s_nop 1
	v_add_f32_dpp v41, v41, v41 row_mirror row_mask:0xf bank_mask:0xf
	s_waitcnt lgkmcnt(0)
	v_add_f32_e32 v41, 0x358637bd, v41
	v_cmp_gt_f32_e32 vcc, s58, v41
	v_mul_f32_e32 v54, 0x4b800000, v41
	s_nop 0
	v_cndmask_b32_e32 v41, v41, v54, vcc
	v_rsq_f32_e32 v41, v41
	s_nop 0
	v_mul_f32_e32 v54, 0x45800000, v41
	v_cndmask_b32_e32 v54, v41, v54, vcc
	v_pk_mul_f32 v[46:47], v[46:47], v[54:55] op_sel_hi:[1,0]
	v_pk_mul_f32 v[48:49], v[48:49], v[54:55] op_sel_hi:[1,0]
	v_cvt_pk_bf16_f32 v46, v46, v47
	v_cvt_pk_bf16_f32 v47, v48, v49
	v_pk_mul_f32 v[48:49], v[50:51], v[54:55] op_sel_hi:[1,0]
	v_pk_mul_f32 v[50:51], v[52:53], v[54:55] op_sel_hi:[1,0]
	v_cvt_pk_bf16_f32 v48, v48, v49
	v_cvt_pk_bf16_f32 v49, v50, v51
	v_mov_b32_e32 v54, 0
	global_store_dwordx4 v[44:45], v[46:49], off offset:1024
	v_mov_b32_e32 v55, 0
	v_mov_b32_e32 v52, 0
	v_mov_b32_e32 v53, 0
	v_mov_b32_e32 v50, 0
	v_mov_b32_e32 v51, v54
	v_mov_b32_e32 v46, v54
	v_mov_b32_e32 v47, v54
	v_mov_b32_e32 v48, 0
	v_mov_b32_e32 v49, 0
	s_and_saveexec_b64 s[26:27], s[42:43]
	s_cbranch_execz .LBB0_898
	v_mad_u64_u32 v[46:47], s[6:7], v62, s57, v[38:39]
	v_mov_b32_e32 v46, v222
	v_mov_b32_e32 v47, v223
	v_mov_b32_e32 v48, v224
	v_mov_b32_e32 v49, v225
	s_nop 0
	v_mov_b32_e32 v54, v140
	v_mov_b32_e32 v55, v141
	v_mov_b32_e32 v56, v142
	v_mov_b32_e32 v57, v143
	v_mov_b32_e32 v64, v144
	v_mov_b32_e32 v65, v145
	v_mov_b32_e32 v66, v146
	v_mov_b32_e32 v67, v147
	v_lshlrev_b32_e32 v50, 16, v46
	v_and_b32_e32 v51, 0xffff0000, v46
	v_lshlrev_b32_e32 v46, 16, v47
	v_and_b32_e32 v47, 0xffff0000, v47
	v_pk_fma_f32 v[52:53], v[64:65], v[50:51], 0 op_sel_hi:[1,1,0]
	v_pk_fma_f32 v[50:51], v[66:67], v[46:47], 0 op_sel_hi:[1,1,0]
	v_lshlrev_b32_e32 v46, 16, v48
	v_and_b32_e32 v47, 0xffff0000, v48
	v_lshlrev_b32_e32 v48, 16, v49
	v_and_b32_e32 v49, 0xffff0000, v49
	v_pk_fma_f32 v[46:47], v[54:55], v[46:47], 0 op_sel_hi:[1,1,0]
	v_pk_fma_f32 v[54:55], v[56:57], v[48:49], 0 op_sel_hi:[1,1,0]
	s_nop 0
	v_mov_b32_e32 v48, v54
	v_mov_b32_e32 v49, v55
	s_or_b64 exec, exec, s[26:27]
	s_and_saveexec_b64 s[26:27], s[44:45]
	s_cbranch_execnz .LBB0_899

; DI float bflo(unsigned u) { return __uint_as_float(u << 16); }
; DI float bfhi(unsigned u) { return __uint_as_float(u & 0xffff0000u); }
; DI void prep_ew_item(const Params& p, int l, int item, bf16_t* lds) {
;     ...
;       for (int i = 0; i < 4; ++i) {
;         const int ts = tl - 3 + i;
;         if (ts >= 0) {
;           u32x4 v = *(const u32x4*)(RC + (size_t)ts * 1536 + ch); unsigned w[4] = {v.x, v.y, v.z, v.w};
;           const float* cw = p.convw + ((size_t)l * 4 + i) * 1536 + ch;
;           f32x4 c0 = *(const f32x4*)cw, c1 = *(const f32x4*)(cw + 4);
;           a[0] += bflo(w[0]) * c0[0]; a[1] += bfhi(w[0]) * c0[1]; a[2] += bflo(w[1]) * c0[2]; a[3] += bfhi(w[1]) * c0[3];
;           a[4] += bflo(w[2]) * c1[0]; a[5] += bfhi(w[2]) * c1[1]; a[6] += bflo(w[3]) * c1[2]; a[7] += bfhi(w[3]) * c1[3];
;         }
.LBB0_897:
	v_mad_u64_u32 v[40:41], s[6:7], v40, s57, v[38:39]
	v_mov_b32_e32 v54, v228
	v_mov_b32_e32 v55, v229
	v_mov_b32_e32 v56, v230
	v_mov_b32_e32 v57, v231
	v_mov_b32_e32 v62, v148
	v_mov_b32_e32 v63, v149
	v_mov_b32_e32 v64, v150
	v_mov_b32_e32 v65, v151
	v_mov_b32_e32 v66, v152
	v_mov_b32_e32 v67, v153
	v_mov_b32_e32 v68, v154
	v_mov_b32_e32 v69, v155
	v_lshlrev_b32_e32 v40, 16, v54
	v_and_b32_e32 v41, 0xffff0000, v54
	v_pk_fma_f32 v[52:53], v[66:67], v[40:41], v[52:53]
	v_lshlrev_b32_e32 v40, 16, v55
	v_and_b32_e32 v41, 0xffff0000, v55
	v_pk_fma_f32 v[50:51], v[68:69], v[40:41], v[50:51]
	v_lshlrev_b32_e32 v40, 16, v56
	v_and_b32_e32 v41, 0xffff0000, v56
	v_pk_fma_f32 v[46:47], v[62:63], v[40:41], v[46:47]
	v_lshlrev_b32_e32 v40, 16, v57
	v_and_b32_e32 v41, 0xffff0000, v57
	v_pk_fma_f32 v[48:49], v[64:65], v[40:41], v[48:49]
	s_or_b64 exec, exec, s[26:27]
	s_and_saveexec_b64 s[26:27], s[48:49]
	s_cbranch_execnz .LBB0_901
	s_branch .LBB0_902

; DI float bflo(unsigned u) { return __uint_as_float(u << 16); }
; DI float bfhi(unsigned u) { return __uint_as_float(u & 0xffff0000u); }
; DI void prep_ew_item(const Params& p, int l, int item, bf16_t* lds) {
;     ...
;       for (int i = 0; i < 4; ++i) {
;         const int ts = tl - 3 + i;
;         if (ts >= 0) {
;           u32x4 v = *(const u32x4*)(RC + (size_t)ts * 1536 + ch); unsigned w[4] = {v.x, v.y, v.z, v.w};
;           const float* cw = p.convw + ((size_t)l * 4 + i) * 1536 + ch;
;           f32x4 c0 = *(const f32x4*)cw, c1 = *(const f32x4*)(cw + 4);
;           a[0] += bflo(w[0]) * c0[0]; a[1] += bfhi(w[0]) * c0[1]; a[2] += bflo(w[1]) * c0[2]; a[3] += bfhi(w[1]) * c0[3];
;           a[4] += bflo(w[2]) * c1[0]; a[5] += bfhi(w[2]) * c1[1]; a[6] += bflo(w[3]) * c1[2]; a[7] += bfhi(w[3]) * c1[3];
;         }
.LBB0_899:
	v_mad_u64_u32 v[48:49], s[6:7], v63, s57, v[38:39]
	v_mov_b32_e32 v62, v214
	v_mov_b32_e32 v63, v215
	v_mov_b32_e32 v64, v216
	v_mov_b32_e32 v65, v217
	v_mov_b32_e32 v66, v156
	v_mov_b32_e32 v67, v157
	v_mov_b32_e32 v68, v158
	v_mov_b32_e32 v69, v159
	v_mov_b32_e32 v70, v160
	v_mov_b32_e32 v71, v161
	v_mov_b32_e32 v72, v162
	v_mov_b32_e32 v73, v163
	v_lshlrev_b32_e32 v48, 16, v62
	v_and_b32_e32 v49, 0xffff0000, v62
	v_pk_fma_f32 v[52:53], v[70:71], v[48:49], v[52:53]
	v_lshlrev_b32_e32 v48, 16, v63
	v_and_b32_e32 v49, 0xffff0000, v63
	v_pk_fma_f32 v[50:51], v[72:73], v[48:49], v[50:51]
	v_lshlrev_b32_e32 v48, 16, v64
	v_and_b32_e32 v49, 0xffff0000, v64
	v_pk_fma_f32 v[46:47], v[66:67], v[48:49], v[46:47]
	v_lshlrev_b32_e32 v48, 16, v65
	v_and_b32_e32 v49, 0xffff0000, v65
	v_pk_fma_f32 v[48:49], v[68:69], v[48:49], v[54:55]
	s_or_b64 exec, exec, s[26:27]
	s_and_saveexec_b64 s[26:27], s[46:47]
	s_cbranch_execnz .LBB0_897

; DI float bflo(unsigned u) { return __uint_as_float(u << 16); }
; DI float bfhi(unsigned u) { return __uint_as_float(u & 0xffff0000u); }
; DI void prep_ew_item(const Params& p, int l, int item, bf16_t* lds) {
;     ...
;       for (int i = 0; i < 4; ++i) {
;         const int ts = tl - 3 + i;
;         if (ts >= 0) {
;           u32x4 v = *(const u32x4*)(RC + (size_t)ts * 1536 + ch); unsigned w[4] = {v.x, v.y, v.z, v.w};
;           const float* cw = p.convw + ((size_t)l * 4 + i) * 1536 + ch;
;           f32x4 c0 = *(const f32x4*)cw, c1 = *(const f32x4*)(cw + 4);
;           a[0] += bflo(w[0]) * c0[0]; a[1] += bfhi(w[0]) * c0[1]; a[2] += bflo(w[1]) * c0[2]; a[3] += bfhi(w[1]) * c0[3];
;           a[4] += bflo(w[2]) * c1[0]; a[5] += bfhi(w[2]) * c1[1]; a[6] += bflo(w[3]) * c1[2]; a[7] += bfhi(w[3]) * c1[3];
;         }
.LBB0_901:
	v_mad_u64_u32 v[40:41], s[6:7], v42, s57, v[38:39]
	v_mov_b32_e32 v54, v246
	v_mov_b32_e32 v55, v247
	v_mov_b32_e32 v56, v248
	v_mov_b32_e32 v57, v249
	v_mov_b32_e32 v62, v164
	v_mov_b32_e32 v63, v165
	v_mov_b32_e32 v64, v166
	v_mov_b32_e32 v65, v167
	v_mov_b32_e32 v66, v168
	v_mov_b32_e32 v67, v169
	v_mov_b32_e32 v68, v170
	v_mov_b32_e32 v69, v171
	v_lshlrev_b32_e32 v40, 16, v54
	v_and_b32_e32 v41, 0xffff0000, v54
	v_pk_fma_f32 v[52:53], v[66:67], v[40:41], v[52:53]
	v_lshlrev_b32_e32 v40, 16, v55
	v_and_b32_e32 v41, 0xffff0000, v55
	v_pk_fma_f32 v[50:51], v[68:69], v[40:41], v[50:51]
	v_lshlrev_b32_e32 v40, 16, v56
	v_and_b32_e32 v41, 0xffff0000, v56
	v_pk_fma_f32 v[46:47], v[62:63], v[40:41], v[46:47]
	v_lshlrev_b32_e32 v40, 16, v57
	v_and_b32_e32 v41, 0xffff0000, v57
	v_pk_fma_f32 v[48:49], v[64:65], v[40:41], v[48:49]
